# v18 + packed f32 ops in the retention / state attention units split into scalar pairs (packed f32 beside MFMAs is the slower form)
# speedup vs baseline: 1.0066x; 1.0066x over previous
.LBB0_200:
	v_add_f32_e32 v118, 0, v117
	v_add_f32_e32 v119, 0x42000000, v118
	v_fma_f32 v119, v119, v104, v105
	v_exp_f32_e32 v120, v119
	v_add_f32_e32 v119, 1.0, v117
	v_fma_f32 v118, v118, v104, v105
	v_add_f32_e32 v121, 0x42000000, v119
	v_fma_f32 v119, v119, v104, v105
	v_exp_f32_e32 v118, v118
	v_exp_f32_e32 v119, v119
	v_fma_f32 v121, v121, v104, v105
	v_exp_f32_e32 v121, v121
	s_add_i32 s36, s36, 1
	v_mul_f32_e32 v48, v48, v118
	v_mul_f32_e32 v49, v49, v119
	v_add_f32_e32 v118, 2.0, v117
	v_add_f32_e32 v119, 0x42000000, v118
	v_fma_f32 v119, v119, v104, v105
	v_mul_f32_e32 v32, v32, v120
	v_mul_f32_e32 v33, v33, v121
	v_exp_f32_e32 v120, v119
	v_add_f32_e32 v119, 0x40400000, v117
	v_fma_f32 v118, v118, v104, v105
	v_add_f32_e32 v121, 0x42000000, v119
	v_fma_f32 v119, v119, v104, v105
	v_exp_f32_e32 v118, v118
	v_exp_f32_e32 v119, v119
	v_fma_f32 v121, v121, v104, v105
	v_exp_f32_e32 v121, v121
	v_cvt_pk_bf16_f32 v32, v32, v33
	v_mul_f32_e32 v50, v50, v118
	v_mul_f32_e32 v51, v51, v119
	v_add_f32_e32 v118, 0x41000000, v117
	v_add_f32_e32 v119, 0x42000000, v118
	v_fma_f32 v119, v119, v104, v105
	v_mul_f32_e32 v34, v34, v120
	v_mul_f32_e32 v35, v35, v121
	v_exp_f32_e32 v120, v119
	v_add_f32_e32 v119, 0x41100000, v117
	v_add_f32_e32 v121, 0x42000000, v119
	v_fma_f32 v118, v118, v104, v105
	v_fma_f32 v119, v119, v104, v105
	v_fma_f32 v121, v121, v104, v105
	v_exp_f32_e32 v118, v118
	v_exp_f32_e32 v119, v119
	v_exp_f32_e32 v121, v121
	v_cvt_pk_bf16_f32 v33, v34, v35
	s_add_i32 s0, s33, 1
	v_mul_f32_e32 v52, v52, v118
	v_mul_f32_e32 v53, v53, v119
	v_mul_f32_e32 v118, v36, v120
	v_mul_f32_e32 v119, v37, v121
	v_add_f32_e32 v36, 0x41200000, v117
	v_add_f32_e32 v37, 0x42000000, v36
	v_fma_f32 v37, v37, v104, v105
	v_exp_f32_e32 v120, v37
	v_add_f32_e32 v37, 0x41300000, v117
	v_fma_f32 v36, v36, v104, v105
	v_add_f32_e32 v121, 0x42000000, v37
	v_fma_f32 v37, v37, v104, v105
	v_exp_f32_e32 v36, v36
	v_exp_f32_e32 v37, v37
	v_fma_f32 v121, v121, v104, v105
	v_exp_f32_e32 v121, v121
	v_cvt_pk_bf16_f32 v34, v118, v119
	v_mul_f32_e32 v54, v54, v36
	v_mul_f32_e32 v55, v55, v37
	v_add_f32_e32 v36, 0x41800000, v117
	v_add_f32_e32 v37, 0x42000000, v36
	v_fma_f32 v37, v37, v104, v105
	v_mul_f32_e32 v120, v38, v120
	v_mul_f32_e32 v121, v39, v121
	v_exp_f32_e32 v38, v37
	v_add_f32_e32 v37, 0x41880000, v117
	v_fma_f32 v36, v36, v104, v105
	v_add_f32_e32 v39, 0x42000000, v37
	v_fma_f32 v37, v37, v104, v105
	v_exp_f32_e32 v36, v36
	v_exp_f32_e32 v37, v37
	v_fma_f32 v39, v39, v104, v105
	v_exp_f32_e32 v39, v39
	v_cvt_pk_bf16_f32 v35, v120, v121
	v_mul_f32_e32 v56, v56, v36
	v_mul_f32_e32 v57, v57, v37
	v_add_f32_e32 v36, 0x41900000, v117
	v_add_f32_e32 v37, 0x42000000, v36
	v_fma_f32 v37, v37, v104, v105
	v_mul_f32_e32 v122, v40, v38
	v_mul_f32_e32 v123, v41, v39
	v_exp_f32_e32 v38, v37
	v_add_f32_e32 v37, 0x41980000, v117
	v_fma_f32 v36, v36, v104, v105
	v_add_f32_e32 v39, 0x42000000, v37
	v_fma_f32 v37, v37, v104, v105
	v_exp_f32_e32 v36, v36
	v_exp_f32_e32 v37, v37
	v_fma_f32 v39, v39, v104, v105
	v_exp_f32_e32 v39, v39
	v_cvt_pk_bf16_f32 v40, v56, v57
	v_mul_f32_e32 v58, v58, v36
	v_mul_f32_e32 v59, v59, v37
	v_add_f32_e32 v36, 0x41c00000, v117
	v_add_f32_e32 v37, 0x42000000, v36
	v_fma_f32 v37, v37, v104, v105
	v_mul_f32_e32 v124, v42, v38
	v_mul_f32_e32 v125, v43, v39
	v_exp_f32_e32 v38, v37
	v_add_f32_e32 v37, 0x41c80000, v117
	v_fma_f32 v36, v36, v104, v105
	v_add_f32_e32 v39, 0x42000000, v37
	v_fma_f32 v37, v37, v104, v105
	v_exp_f32_e32 v36, v36
	v_exp_f32_e32 v37, v37
	v_fma_f32 v39, v39, v104, v105
	v_exp_f32_e32 v39, v39
	v_cvt_pk_bf16_f32 v41, v58, v59
	v_mul_f32_e32 v42, v60, v36
	v_mul_f32_e32 v43, v61, v37
	v_add_f32_e32 v36, 0x41d00000, v117
	v_add_f32_e32 v37, 0x42000000, v36
	v_fma_f32 v37, v37, v104, v105
	v_mul_f32_e32 v60, v44, v38
	v_mul_f32_e32 v61, v45, v39
	v_exp_f32_e32 v38, v37
	v_add_f32_e32 v37, 0x41d80000, v117
	v_add_f32_e32 v39, 0x42000000, v37
	v_fma_f32 v36, v36, v104, v105
	v_fma_f32 v37, v37, v104, v105
	v_fma_f32 v39, v39, v104, v105
	v_exp_f32_e32 v36, v36
	v_exp_f32_e32 v37, v37
	v_exp_f32_e32 v39, v39
	v_cvt_pk_bf16_f32 v42, v42, v43
	s_cmp_lg_u32 s33, 2
	v_mul_f32_e32 v44, v62, v36
	v_mul_f32_e32 v45, v63, v37
	v_mul_f32_e32 v62, v46, v38
	v_mul_f32_e32 v63, v47, v39
	v_cvt_pk_bf16_f32 v36, v48, v49
	v_cvt_pk_bf16_f32 v37, v50, v51
	v_cvt_pk_bf16_f32 v38, v52, v53
	v_cvt_pk_bf16_f32 v39, v54, v55
	v_cvt_pk_bf16_f32 v46, v60, v61
	v_cvt_pk_bf16_f32 v47, v62, v63
	s_waitcnt lgkmcnt(6)
	v_mfma_f32_32x32x16_bf16 v[16:31], v[36:39], v[94:97], v[16:31]
	ds_read_b64_tr_b16 v[48:49], v116 offset:16384
	ds_read_b64_tr_b16 v[50:51], v116 offset:16896
	ds_read_b64_tr_b16 v[52:53], v116 offset:17408
	ds_read_b64_tr_b16 v[54:55], v116 offset:17920
	ds_read_b64_tr_b16 v[56:57], v116 offset:18432
	ds_read_b64_tr_b16 v[58:59], v116 offset:18944
	ds_read_b64_tr_b16 v[60:61], v116 offset:19456
	ds_read_b64_tr_b16 v[62:63], v116 offset:19968
	v_cvt_pk_bf16_f32 v43, v44, v45
	v_cvt_pk_bf16_f32 v44, v122, v123
	v_cvt_pk_bf16_f32 v45, v124, v125
	s_cselect_b32 s33, s0, 0
	s_mov_b64 s[0:1], 0x8000
	v_lshl_add_u64 v[100:101], v[100:101], 0, s[0:1]
	s_waitcnt lgkmcnt(6)
	v_mfma_f32_32x32x16_bf16 v[0:15], v[36:39], v[48:51], v[0:15]
	v_lshl_add_u64 v[102:103], v[102:103], 0, s[0:1]
	v_add_u32_e32 v115, 64, v115
	s_cmp_eq_u32 s36, 3
	v_mfma_f32_32x32x16_bf16 v[16:31], v[40:43], v[90:93], v[16:31]
	s_waitcnt lgkmcnt(4)
	v_mfma_f32_32x32x16_bf16 v[0:15], v[40:43], v[52:55], v[0:15]
	v_mfma_f32_32x32x16_bf16 v[16:31], v[32:35], v[86:89], v[16:31]
	s_waitcnt lgkmcnt(2)
	v_mfma_f32_32x32x16_bf16 v[0:15], v[32:35], v[56:59], v[0:15]
	v_mfma_f32_32x32x16_bf16 v[16:31], v[44:47], v[82:85], v[16:31]
	s_waitcnt lgkmcnt(0)
	v_mfma_f32_32x32x16_bf16 v[0:15], v[44:47], v[60:63], v[0:15]
	s_cbranch_scc1 .LBB0_203

.LBB0_203:
	v_add_u32_e32 v56, 0, v112
	s_waitcnt vmcnt(0)
	s_barrier
	v_add_u32_e32 v36, v56, v113
	ds_read_b128 v[32:35], v36 offset:4096
	ds_read_b128 v[48:51], v36
	v_add_u32_e32 v57, v56, v114
	ds_read_b128 v[52:55], v57 offset:4096
	ds_read_b128 v[94:97], v57
	v_add_u32_e32 v58, v56, v111
	s_waitcnt lgkmcnt(3)
	v_mfma_f32_32x32x16_bf16 v[32:47], v[32:35], v[76:79], 0
	v_add_u32_e32 v56, v56, v110
	v_readlane_b32 s0, v255, 2
	v_readlane_b32 s1, v255, 3
	s_andn2_b64 vcc, exec, s[0:1]
	ds_read_b128 v[100:103], v58
	s_waitcnt lgkmcnt(2)
	v_mfma_f32_32x32x16_bf16 v[32:47], v[52:55], v[72:75], v[32:47]
	ds_read_b128 v[52:55], v58 offset:4096
	s_waitcnt lgkmcnt(0)
	v_mfma_f32_32x32x16_bf16 v[32:47], v[52:55], v[68:71], v[32:47]
	ds_read_b128 v[52:55], v56 offset:4096
	ds_read_b128 v[110:113], v56
	s_waitcnt lgkmcnt(1)
	v_mfma_f32_32x32x16_bf16 v[32:47], v[52:55], v[64:67], v[32:47]
	v_add_u32_e32 v52, 0, v108
	v_add3_u32 v106, v52, v109, v106
	ds_read_b64_tr_b16 v[90:91], v106 offset:12288
	ds_read_b64_tr_b16 v[92:93], v106 offset:12800
	ds_read_b64_tr_b16 v[82:83], v106 offset:13312
	ds_read_b64_tr_b16 v[84:85], v106 offset:13824
	v_mfma_f32_32x32x16_bf16 v[48:63], v[48:51], v[76:79], 0
	v_add_u32_e32 v76, 0xc0, v107
	v_cvt_f32_i32_e32 v107, v76
	ds_read_b64_tr_b16 v[86:87], v106 offset:14336
	ds_read_b64_tr_b16 v[88:89], v106 offset:14848
	ds_read_b64_tr_b16 v[76:77], v106 offset:15360
	ds_read_b64_tr_b16 v[78:79], v106 offset:15872
	v_mfma_f32_32x32x16_bf16 v[48:63], v[94:97], v[72:75], v[48:63]
	v_add_f32_e32 v74, 0x41d00000, v107
	v_add_f32_e32 v75, 0x41d80000, v107
	v_add_f32_e32 v72, 0x42000000, v74
	v_add_f32_e32 v73, 0x42000000, v75
	v_fma_f32 v72, v72, v104, v105
	v_fma_f32 v73, v73, v104, v105
	v_exp_f32_e32 v72, v72
	v_mfma_f32_32x32x16_bf16 v[48:63], v[100:103], v[68:71], v[48:63]
	v_exp_f32_e32 v73, v73
	s_nop 0
	v_mul_f32_e32 v68, v46, v72
	v_mul_f32_e32 v69, v47, v73
	v_fma_f32 v46, v74, v104, v105
	v_fma_f32 v47, v75, v104, v105
	s_waitcnt lgkmcnt(8)
	v_mfma_f32_32x32x16_bf16 v[48:63], v[110:113], v[64:67], v[48:63]
	v_exp_f32_e32 v46, v46
	v_exp_f32_e32 v47, v47
	v_add_f32_e32 v65, 0x41c80000, v107
	v_add_f32_e32 v67, 0x41980000, v107
	v_add_f32_e32 v74, 0x41200000, v107
	v_add_f32_e32 v75, 0x41300000, v107
	v_add_f32_e32 v72, 0x42000000, v74
	s_nop 4
	v_mul_f32_e32 v62, v62, v46
	v_mul_f32_e32 v63, v63, v47
	v_add_f32_e32 v46, 0x41c00000, v107
	v_add_f32_e32 v47, 0x42000000, v46
	v_fma_f32 v47, v47, v104, v105
	v_exp_f32_e32 v64, v47
	v_fma_f32 v46, v46, v104, v105
	v_fma_f32 v47, v65, v104, v105
	v_exp_f32_e32 v46, v46
	v_exp_f32_e32 v47, v47
	v_add_f32_e32 v73, 0x42000000, v75
	v_fma_f32 v74, v74, v104, v105
	v_fma_f32 v75, v75, v104, v105
	v_mul_f32_e32 v60, v60, v46
	v_mul_f32_e32 v61, v61, v47
	v_add_f32_e32 v46, 0x41900000, v107
	v_add_f32_e32 v47, 0x42000000, v46
	v_fma_f32 v47, v47, v104, v105
	v_exp_f32_e32 v66, v47
	v_fma_f32 v46, v46, v104, v105
	v_fma_f32 v47, v67, v104, v105
	v_exp_f32_e32 v46, v46
	v_exp_f32_e32 v47, v47
	v_exp_f32_e32 v74, v74
	v_exp_f32_e32 v75, v75
	v_fma_f32 v72, v72, v104, v105
	v_mul_f32_e32 v58, v58, v46
	v_mul_f32_e32 v59, v59, v47
	v_add_f32_e32 v46, 0x41800000, v107
	v_add_f32_e32 v47, 0x42000000, v46
	v_fma_f32 v47, v47, v104, v105
	v_exp_f32_e32 v70, v47
	v_add_f32_e32 v47, 0x41880000, v107
	v_add_f32_e32 v71, 0x42000000, v47
	v_fma_f32 v46, v46, v104, v105
	v_fma_f32 v47, v47, v104, v105
	v_exp_f32_e32 v46, v46
	v_exp_f32_e32 v47, v47
	v_mul_f32_e32 v54, v54, v74
	v_mul_f32_e32 v55, v55, v75
	v_add_f32_e32 v74, 2.0, v107
	v_fma_f32 v73, v73, v104, v105
	v_add_f32_e32 v75, 0x42000000, v74
	v_exp_f32_e32 v72, v72
	v_exp_f32_e32 v73, v73
	v_fma_f32 v96, v75, v104, v105
	v_add_f32_e32 v75, 0x40400000, v107
	v_mul_f32_e32 v56, v56, v46
	v_mul_f32_e32 v57, v57, v47
	v_add_f32_e32 v46, 0x41000000, v107
	v_add_f32_e32 v94, 0x42000000, v75
	v_add_f32_e32 v47, 0x42000000, v46
	v_fma_f32 v97, v94, v104, v105
	v_add_f32_e32 v94, 0, v107
	v_fma_f32 v47, v47, v104, v105
	v_add_f32_e32 v95, 0x42000000, v94
	v_mul_f32_e32 v38, v38, v72
	v_mul_f32_e32 v39, v39, v73
	v_exp_f32_e32 v72, v47
	v_add_f32_e32 v47, 0x41100000, v107
	v_fma_f32 v100, v95, v104, v105
	v_add_f32_e32 v95, 1.0, v107
	v_add_f32_e32 v65, 0x42000000, v65
	v_add_f32_e32 v67, 0x42000000, v67
	v_add_f32_e32 v73, 0x42000000, v47
	v_add_f32_e32 v101, 0x42000000, v95
	v_fma_f32 v65, v65, v104, v105
	v_fma_f32 v67, v67, v104, v105
	v_fma_f32 v71, v71, v104, v105
	v_fma_f32 v73, v73, v104, v105
	v_fma_f32 v46, v46, v104, v105
	v_fma_f32 v47, v47, v104, v105
	v_fma_f32 v74, v74, v104, v105
	v_fma_f32 v75, v75, v104, v105
	v_fma_f32 v101, v101, v104, v105
	v_fma_f32 v94, v94, v104, v105
	v_fmac_f32_e32 v105, v95, v104
	v_exp_f32_e32 v46, v46
	v_exp_f32_e32 v47, v47
	v_exp_f32_e32 v94, v94
	v_exp_f32_e32 v95, v105
	v_exp_f32_e32 v74, v74
	v_exp_f32_e32 v75, v75
	v_exp_f32_e32 v73, v73
	v_mul_f32_e32 v52, v52, v46
	v_mul_f32_e32 v53, v53, v47
	v_exp_f32_e32 v96, v96
	v_mul_f32_e32 v46, v48, v94
	v_mul_f32_e32 v47, v49, v95
	v_cvt_pk_bf16_f32 v49, v54, v55
	v_exp_f32_e32 v97, v97
	v_exp_f32_e32 v54, v100
	v_exp_f32_e32 v55, v101
	v_exp_f32_e32 v67, v67
	v_exp_f32_e32 v71, v71
	v_mul_f32_e32 v50, v50, v74
	v_mul_f32_e32 v51, v51, v75
	v_cvt_pk_bf16_f32 v46, v46, v47
	v_cvt_pk_bf16_f32 v47, v50, v51
	v_cvt_pk_bf16_f32 v48, v52, v53
	v_mul_f32_e32 v36, v36, v72
	v_mul_f32_e32 v37, v37, v73
	v_mul_f32_e32 v34, v34, v96
	v_mul_f32_e32 v35, v35, v97
	v_mul_f32_e32 v32, v32, v54
	v_mul_f32_e32 v33, v33, v55
	v_mul_f32_e32 v42, v42, v66
	v_mul_f32_e32 v43, v43, v67
	v_cvt_pk_bf16_f32 v32, v32, v33
	v_cvt_pk_bf16_f32 v33, v34, v35
	v_cvt_pk_bf16_f32 v34, v36, v37
	v_mul_f32_e32 v36, v40, v70
	v_mul_f32_e32 v37, v41, v71
	v_cvt_pk_bf16_f32 v50, v56, v57
	v_cvt_pk_bf16_f32 v36, v36, v37
	v_cvt_pk_bf16_f32 v37, v42, v43
	ds_read_b64_tr_b16 v[40:41], v106 offset:16384
	ds_read_b64_tr_b16 v[42:43], v106 offset:16896
	ds_read_b64_tr_b16 v[54:55], v106 offset:17408
	ds_read_b64_tr_b16 v[56:57], v106 offset:17920
	s_waitcnt lgkmcnt(10)
	v_mfma_f32_32x32x16_bf16 v[16:31], v[46:49], v[90:93], v[16:31]
	v_cvt_pk_bf16_f32 v51, v58, v59
	v_cvt_pk_bf16_f32 v52, v60, v61
	v_cvt_pk_bf16_f32 v53, v62, v63
	v_exp_f32_e32 v65, v65
	v_cvt_pk_bf16_f32 v35, v38, v39
	v_mul_f32_e32 v38, v44, v64
	v_mul_f32_e32 v39, v45, v65
	s_waitcnt lgkmcnt(2)
	v_mfma_f32_32x32x16_bf16 v[0:15], v[46:49], v[40:43], v[0:15]
	ds_read_b64_tr_b16 v[40:41], v106 offset:18432
	ds_read_b64_tr_b16 v[42:43], v106 offset:18944
	ds_read_b64_tr_b16 v[44:45], v106 offset:19456
	ds_read_b64_tr_b16 v[46:47], v106 offset:19968
	v_cvt_pk_bf16_f32 v38, v38, v39
	v_cvt_pk_bf16_f32 v39, v68, v69
	v_mfma_f32_32x32x16_bf16 v[16:31], v[50:53], v[82:85], v[16:31]
	s_waitcnt lgkmcnt(4)
	v_mfma_f32_32x32x16_bf16 v[0:15], v[50:53], v[54:57], v[0:15]
	v_mfma_f32_32x32x16_bf16 v[16:31], v[32:35], v[86:89], v[16:31]
	s_waitcnt lgkmcnt(2)
	v_mfma_f32_32x32x16_bf16 v[0:15], v[32:35], v[40:43], v[0:15]
	v_mfma_f32_32x32x16_bf16 v[16:31], v[36:39], v[76:79], v[16:31]
	s_waitcnt lgkmcnt(0)
	v_mfma_f32_32x32x16_bf16 v[0:15], v[36:39], v[44:47], v[0:15]
	s_cbranch_vccnz .LBB0_205
	s_lshl_b32 s0, s2, 3
	s_or_b32 s36, s0, s3
	s_ashr_i32 s37, s36, 31
	s_lshl_b64 s[36:37], s[36:37], 14
	v_readlane_b32 s0, v255, 6
	s_add_u32 s36, s0, s36
	v_readlane_b32 s0, v255, 7
	v_lshlrev_b32_e32 v32, 2, v80
	s_addc_u32 s37, s0, s37
	v_ashrrev_i32_e32 v99, 31, v98
	v_ashrrev_i32_e32 v33, 31, v32
	v_or_b32_e32 v38, 1, v32
	v_lshl_add_u64 v[34:35], v[98:99], 2, s[36:37]
	v_lshlrev_b64 v[36:37], 8, v[32:33]
	v_ashrrev_i32_e32 v39, 31, v38
	v_lshl_add_u64 v[36:37], v[34:35], 0, v[36:37]
	v_lshlrev_b64 v[38:39], 8, v[38:39]
	global_store_dword v[36:37], v16, off
	v_lshl_add_u64 v[38:39], v[34:35], 0, v[38:39]
	v_or_b32_e32 v16, 2, v32
	global_store_dword v[38:39], v17, off
	v_ashrrev_i32_e32 v17, 31, v16
	v_or_b32_e32 v40, 3, v32
	v_lshlrev_b64 v[16:17], 8, v[16:17]
	v_ashrrev_i32_e32 v41, 31, v40
	v_lshl_add_u64 v[16:17], v[34:35], 0, v[16:17]
	v_lshlrev_b64 v[40:41], 8, v[40:41]
	global_store_dword v[16:17], v18, off
	v_lshl_add_u64 v[40:41], v[34:35], 0, v[40:41]
	v_add_u32_e32 v18, 8, v32
	global_store_dword v[40:41], v19, off
	v_ashrrev_i32_e32 v19, 31, v18
	v_add_u32_e32 v42, 9, v32
	v_lshlrev_b64 v[18:19], 8, v[18:19]
	v_ashrrev_i32_e32 v43, 31, v42
	v_lshl_add_u64 v[18:19], v[34:35], 0, v[18:19]
	v_lshlrev_b64 v[42:43], 8, v[42:43]
	global_store_dword v[18:19], v20, off
	v_lshl_add_u64 v[42:43], v[34:35], 0, v[42:43]
	v_add_u32_e32 v20, 10, v32
	global_store_dword v[42:43], v21, off
	v_ashrrev_i32_e32 v21, 31, v20
	v_add_u32_e32 v44, 11, v32
	v_lshlrev_b64 v[20:21], 8, v[20:21]
	v_ashrrev_i32_e32 v45, 31, v44
	v_lshl_add_u64 v[20:21], v[34:35], 0, v[20:21]
	v_lshlrev_b64 v[44:45], 8, v[44:45]
	global_store_dword v[20:21], v22, off
	v_lshl_add_u64 v[44:45], v[34:35], 0, v[44:45]
	v_add_u32_e32 v22, 16, v32
	global_store_dword v[44:45], v23, off
	v_ashrrev_i32_e32 v23, 31, v22
	v_add_u32_e32 v46, 17, v32
	v_lshlrev_b64 v[22:23], 8, v[22:23]
	v_ashrrev_i32_e32 v47, 31, v46
	v_lshl_add_u64 v[22:23], v[34:35], 0, v[22:23]
	v_lshlrev_b64 v[46:47], 8, v[46:47]
	global_store_dword v[22:23], v24, off
	v_lshl_add_u64 v[46:47], v[34:35], 0, v[46:47]
	v_add_u32_e32 v24, 18, v32
	global_store_dword v[46:47], v25, off
	v_ashrrev_i32_e32 v25, 31, v24
	v_add_u32_e32 v48, 19, v32
	v_lshlrev_b64 v[24:25], 8, v[24:25]
	v_ashrrev_i32_e32 v49, 31, v48
	v_lshl_add_u64 v[24:25], v[34:35], 0, v[24:25]
	v_lshlrev_b64 v[48:49], 8, v[48:49]
	global_store_dword v[24:25], v26, off
	v_lshl_add_u64 v[48:49], v[34:35], 0, v[48:49]
	v_add_u32_e32 v26, 24, v32
	global_store_dword v[48:49], v27, off
	v_ashrrev_i32_e32 v27, 31, v26
	v_add_u32_e32 v50, 25, v32
	v_lshlrev_b64 v[26:27], 8, v[26:27]
	v_ashrrev_i32_e32 v51, 31, v50
	v_lshl_add_u64 v[26:27], v[34:35], 0, v[26:27]
	v_lshlrev_b64 v[50:51], 8, v[50:51]
	global_store_dword v[26:27], v28, off
	v_lshl_add_u64 v[50:51], v[34:35], 0, v[50:51]
	v_add_u32_e32 v28, 26, v32
	v_add_u32_e32 v32, 27, v32
	global_store_dword v[50:51], v29, off
	v_ashrrev_i32_e32 v29, 31, v28
	v_ashrrev_i32_e32 v33, 31, v32
	v_lshlrev_b64 v[28:29], 8, v[28:29]
	v_lshlrev_b64 v[32:33], 8, v[32:33]
	v_lshl_add_u64 v[28:29], v[34:35], 0, v[28:29]
	v_lshl_add_u64 v[32:33], v[34:35], 0, v[32:33]
	global_store_dword v[28:29], v30, off
	global_store_dword v[32:33], v31, off
	global_store_dword v[36:37], v0, off offset:128
	global_store_dword v[38:39], v1, off offset:128
	global_store_dword v[16:17], v2, off offset:128
	global_store_dword v[40:41], v3, off offset:128
	global_store_dword v[18:19], v4, off offset:128
	global_store_dword v[42:43], v5, off offset:128
	global_store_dword v[20:21], v6, off offset:128
	global_store_dword v[44:45], v7, off offset:128
	global_store_dword v[22:23], v8, off offset:128
	global_store_dword v[46:47], v9, off offset:128
	global_store_dword v[24:25], v10, off offset:128
	global_store_dword v[48:49], v11, off offset:128
	global_store_dword v[26:27], v12, off offset:128
	global_store_dword v[50:51], v13, off offset:128
	global_store_dword v[28:29], v14, off offset:128
	global_store_dword v[32:33], v15, off offset:128

.LBB0_231:
	s_nop 5
	v_mul_f32_e32 v36, v54, v70
	v_mul_f32_e32 v37, v55, v71
	v_mul_f32_e32 v34, v52, v68
	v_mul_f32_e32 v35, v53, v69
	v_mul_f32_e32 v38, v50, v66
	v_mul_f32_e32 v39, v51, v67
	v_mul_f32_e32 v32, v48, v64
	v_mul_f32_e32 v33, v49, v65
	v_cvt_pk_bf16_f32 v34, v34, v35
	v_cvt_pk_bf16_f32 v32, v32, v33
	v_cvt_pk_bf16_f32 v33, v38, v39
	v_cvt_pk_bf16_f32 v35, v36, v37
	ds_read_b64_tr_b16 v[48:49], v153 offset:16384
	ds_read_b64_tr_b16 v[50:51], v153 offset:16896
	ds_read_b64_tr_b16 v[52:53], v153 offset:17408
	ds_read_b64_tr_b16 v[54:55], v153 offset:17920
	s_waitcnt lgkmcnt(10)
	v_mfma_f32_32x32x16_bf16 v[16:31], v[32:35], v[110:113], v[16:31]
	v_mul_f32_e64 v40, v62, v78
	v_mul_f32_e64 v41, v63, v79
	v_mul_f32_e64 v38, v60, v76
	v_mul_f32_e64 v39, v61, v77
	v_mul_f32_e64 v42, v58, v74
	v_mul_f32_e64 v43, v59, v75
	v_mul_f32_e32 v36, v56, v72
	v_mul_f32_e32 v37, v57, v73
	v_cvt_pk_bf16_f32 v38, v38, v39
	v_cvt_pk_bf16_f32 v36, v36, v37
	v_cvt_pk_bf16_f32 v37, v42, v43
	s_waitcnt lgkmcnt(2)
	v_mfma_f32_32x32x16_bf16 v[0:15], v[32:35], v[48:51], v[0:15]
	v_cvt_pk_bf16_f32 v39, v40, v41
	v_cvt_pk_bf16_f32 v40, v122, v123
	v_cvt_pk_bf16_f32 v41, v124, v125
	v_cvt_pk_bf16_f32 v42, v126, v127
	v_cvt_pk_bf16_f32 v43, v128, v129
	v_mul_f32_e32 v47, v47, v155
	v_cvt_pk_bf16_f32 v44, v130, v131
	v_mfma_f32_32x32x16_bf16 v[16:31], v[36:39], v[106:109], v[16:31]
	v_cvt_pk_bf16_f32 v45, v132, v133
	v_cvt_pk_bf16_f32 v46, v134, v135
	v_cvt_pk_bf16_f32 v47, v154, v47
	s_add_i32 s0, s60, 1
	s_cmp_lg_u32 s60, 2
	s_cselect_b32 s60, s0, 0
	s_add_i32 s41, s41, 64
	s_waitcnt lgkmcnt(0)
	v_mfma_f32_32x32x16_bf16 v[0:15], v[36:39], v[52:55], v[0:15]
	ds_read_b64_tr_b16 v[32:33], v153 offset:18432
	ds_read_b64_tr_b16 v[34:35], v153 offset:18944
	ds_read_b64_tr_b16 v[36:37], v153 offset:19456
	ds_read_b64_tr_b16 v[38:39], v153 offset:19968
	s_mov_b64 s[0:1], 0x8000
	s_add_i32 s54, s54, 1
	s_add_i32 s65, s65, 1
	v_lshl_add_u64 v[118:119], v[118:119], 0, s[0:1]
	v_lshl_add_u64 v[120:121], v[120:121], 0, s[0:1]
	v_subrev_u32_e32 v152, 64, v152
	v_mfma_f32_32x32x16_bf16 v[16:31], v[40:43], v[102:105], v[16:31]
	s_cmp_eq_u32 s55, s41
	s_waitcnt lgkmcnt(2)
	v_mfma_f32_32x32x16_bf16 v[0:15], v[40:43], v[32:35], v[0:15]
	v_mfma_f32_32x32x16_bf16 v[16:31], v[44:47], v[98:101], v[16:31]
	s_waitcnt lgkmcnt(0)
	v_mfma_f32_32x32x16_bf16 v[0:15], v[44:47], v[36:39], v[0:15]
	s_cbranch_scc1 .LBB0_242
.LBB0_232:
	s_mul_i32 s66, s60, 0x5000
	s_add_i32 s0, s66, 0
	v_add_u32_e32 v36, s0, v144
	s_waitcnt vmcnt(2)
	s_barrier
	v_add_u32_e32 v32, v36, v151
	ds_read_b128 v[48:51], v32
	ds_read_b128 v[32:35], v32 offset:4096
	v_add_u32_e32 v37, v36, v145
	ds_read_b128 v[64:67], v37
	ds_read_b128 v[52:55], v37 offset:4096
	v_add_u32_e32 v37, v36, v146
	v_add_u32_e32 v36, v36, v147
	ds_read_b128 v[68:71], v37
	ds_read_b128 v[56:59], v37 offset:4096
	ds_read_b128 v[72:75], v36
	ds_read_b128 v[60:63], v36 offset:4096
	s_waitcnt lgkmcnt(0)
	v_mfma_f32_32x32x16_bf16 v[32:47], v[32:35], v[94:97], 0
	v_mfma_f32_32x32x16_bf16 v[32:47], v[52:55], v[90:93], v[32:47]
	v_add3_u32 v52, s0, v117, v143
	v_add_u32_e32 v153, v52, v142
	ds_read_b64_tr_b16 v[110:111], v153 offset:12288
	ds_read_b64_tr_b16 v[112:113], v153 offset:12800
	ds_read_b64_tr_b16 v[106:107], v153 offset:13312
	ds_read_b64_tr_b16 v[108:109], v153 offset:13824
	ds_read_b64_tr_b16 v[102:103], v153 offset:14336
	ds_read_b64_tr_b16 v[104:105], v153 offset:14848
	ds_read_b64_tr_b16 v[98:99], v153 offset:15360
	ds_read_b64_tr_b16 v[100:101], v153 offset:15872
	s_add_i32 s0, s41, 63
	s_cmp_ge_u32 s0, s33
	s_cselect_b64 s[58:59], -1, 0
	s_cmp_lt_u32 s0, s33
	v_mfma_f32_32x32x16_bf16 v[32:47], v[56:59], v[86:89], v[32:47]
	s_cselect_b64 s[62:63], -1, 0
	s_cmp_gt_u32 s41, s50
	s_cselect_b64 s[72:73], -1, 0
	s_or_b64 s[72:73], s[62:63], s[72:73]
	s_mov_b64 s[62:63], -1
	s_andn2_b64 vcc, exec, s[72:73]
	v_mfma_f32_32x32x16_bf16 v[32:47], v[60:63], v[82:85], v[32:47]
	v_mfma_f32_32x32x16_bf16 v[48:63], v[48:51], v[94:97], 0
	v_mfma_f32_32x32x16_bf16 v[48:63], v[64:67], v[90:93], v[48:63]
	v_mfma_f32_32x32x16_bf16 v[48:63], v[68:71], v[86:89], v[48:63]
	v_mfma_f32_32x32x16_bf16 v[48:63], v[72:75], v[82:85], v[48:63]
	s_cbranch_vccz .LBB0_235
	v_cvt_f32_i32_e32 v64, v152
	s_mov_b32 s0, 0xc2000000
	v_cmp_lt_f32_e32 vcc, 0, v64
	v_add_f32_e32 v65, -1.0, v64
	s_mov_b32 s62, -2.0
	v_cndmask_b32_e32 v66, v137, v115, vcc
	v_mul_f32_e64 v66, |v64|, v66
	v_cmp_lt_f32_e32 vcc, 0, v65
	v_exp_f32_e32 v155, v66
	s_mov_b32 s63, 0xc0400000
	v_cndmask_b32_e32 v66, v137, v115, vcc
	v_mul_f32_e64 v66, |v65|, v66
	v_exp_f32_e32 v156, v66
	v_add_f32_e32 v66, s0, v64
	v_add_f32_e32 v67, s0, v65
	s_nop 0
	v_cmp_lt_f32_e32 vcc, 0, v66
	s_nop 1
	v_cndmask_b32_e32 v68, v137, v115, vcc
	v_cmp_lt_f32_e32 vcc, 0, v67
	v_mul_f32_e64 v68, |v66|, v68
	v_exp_f32_e32 v68, v68
	v_cndmask_b32_e32 v69, v137, v115, vcc
	v_mul_f32_e64 v69, |v67|, v69
	v_exp_f32_e32 v69, v69
	v_cmp_neq_f32_e32 vcc, 0, v67
	s_nop 1
	v_cndmask_b32_e32 v67, 2.0, v69, vcc
	v_cmp_neq_f32_e32 vcc, 0, v66
	s_nop 1
	v_cndmask_b32_e32 v66, 2.0, v68, vcc
	v_mul_f32_e32 v122, v32, v66
	v_mul_f32_e32 v123, v33, v67
	v_add_f32_e32 v66, s62, v64
	v_add_f32_e32 v67, s63, v64
	v_cmp_lt_f32_e32 vcc, 0, v66
	s_mov_b32 s62, 0xc1000000
	s_mov_b32 s63, 0xc1100000
	v_cndmask_b32_e32 v68, v137, v115, vcc
	v_mul_f32_e64 v68, |v66|, v68
	v_cmp_lt_f32_e32 vcc, 0, v67
	v_exp_f32_e32 v157, v68
	s_nop 0
	v_cndmask_b32_e32 v68, v137, v115, vcc
	v_mul_f32_e64 v68, |v67|, v68
	v_exp_f32_e32 v158, v68
	v_add_f32_e32 v68, s0, v66
	v_add_f32_e32 v69, s0, v67
	s_nop 0
	v_cmp_lt_f32_e32 vcc, 0, v68
	s_nop 1
	v_cndmask_b32_e32 v70, v137, v115, vcc
	v_cmp_lt_f32_e32 vcc, 0, v69
	v_mul_f32_e64 v70, |v68|, v70
	v_exp_f32_e32 v70, v70
	v_cndmask_b32_e32 v71, v137, v115, vcc
	v_mul_f32_e64 v71, |v69|, v71
	v_exp_f32_e32 v71, v71
	v_cmp_neq_f32_e32 vcc, 0, v69
	s_nop 1
	v_cndmask_b32_e32 v69, 2.0, v71, vcc
	v_cmp_neq_f32_e32 vcc, 0, v68
	s_nop 1
	v_cndmask_b32_e32 v68, 2.0, v70, vcc
	v_mul_f32_e32 v124, v34, v68
	v_mul_f32_e32 v125, v35, v69
	v_add_f32_e32 v68, s62, v64
	v_add_f32_e32 v69, s63, v64
	v_cmp_lt_f32_e32 vcc, 0, v68
	s_mov_b32 s62, 0xc1200000
	s_mov_b32 s63, 0xc1300000
	v_cndmask_b32_e32 v70, v137, v115, vcc
	v_mul_f32_e64 v70, |v68|, v70
	v_cmp_lt_f32_e32 vcc, 0, v69
	v_exp_f32_e32 v159, v70
	s_nop 0
	v_cndmask_b32_e32 v70, v137, v115, vcc
	v_mul_f32_e64 v70, |v69|, v70
	v_exp_f32_e32 v160, v70
	v_add_f32_e32 v70, s0, v68
	v_add_f32_e32 v71, s0, v69
	s_nop 0
	v_cmp_lt_f32_e32 vcc, 0, v70
	s_nop 1
	v_cndmask_b32_e32 v72, v137, v115, vcc
	v_cmp_lt_f32_e32 vcc, 0, v71
	v_mul_f32_e64 v72, |v70|, v72
	v_exp_f32_e32 v72, v72
	v_cndmask_b32_e32 v73, v137, v115, vcc
	v_mul_f32_e64 v73, |v71|, v73
	v_exp_f32_e32 v73, v73
	v_cmp_neq_f32_e32 vcc, 0, v71
	s_nop 1
	v_cndmask_b32_e32 v71, 2.0, v73, vcc
	v_cmp_neq_f32_e32 vcc, 0, v70
	s_nop 1
	v_cndmask_b32_e32 v70, 2.0, v72, vcc
	v_mul_f32_e32 v126, v36, v70
	v_mul_f32_e32 v127, v37, v71
	v_add_f32_e32 v70, s62, v64
	v_add_f32_e32 v71, s63, v64
	v_cmp_lt_f32_e32 vcc, 0, v70
	s_mov_b32 s62, 0xc1800000
	s_mov_b32 s63, 0xc1880000
	v_cndmask_b32_e32 v72, v137, v115, vcc
	v_mul_f32_e64 v72, |v70|, v72
	v_cmp_lt_f32_e32 vcc, 0, v71
	v_exp_f32_e32 v161, v72
	s_nop 0
	v_cndmask_b32_e32 v72, v137, v115, vcc
	v_mul_f32_e64 v72, |v71|, v72
	v_exp_f32_e32 v162, v72
	v_add_f32_e32 v72, s0, v70
	v_add_f32_e32 v73, s0, v71
	s_nop 0
	v_cmp_lt_f32_e32 vcc, 0, v72
	s_nop 1
	v_cndmask_b32_e32 v74, v137, v115, vcc
	v_cmp_lt_f32_e32 vcc, 0, v73
	v_mul_f32_e64 v74, |v72|, v74
	v_exp_f32_e32 v74, v74
	v_cndmask_b32_e32 v75, v137, v115, vcc
	v_mul_f32_e64 v75, |v73|, v75
	v_exp_f32_e32 v75, v75
	v_cmp_neq_f32_e32 vcc, 0, v73
	s_nop 1
	v_cndmask_b32_e32 v73, 2.0, v75, vcc
	v_cmp_neq_f32_e32 vcc, 0, v72
	s_nop 1
	v_cndmask_b32_e32 v72, 2.0, v74, vcc
	v_mul_f32_e32 v128, v38, v72
	v_mul_f32_e32 v129, v39, v73
	v_add_f32_e32 v72, s62, v64
	v_add_f32_e32 v73, s63, v64
	v_cmp_lt_f32_e32 vcc, 0, v72
	s_mov_b32 s62, 0xc1900000
	s_mov_b32 s63, 0xc1980000
	v_cndmask_b32_e32 v74, v137, v115, vcc
	v_mul_f32_e64 v74, |v72|, v74
	v_cmp_lt_f32_e32 vcc, 0, v73
	v_exp_f32_e32 v163, v74
	s_nop 0
	v_cndmask_b32_e32 v74, v137, v115, vcc
	v_mul_f32_e64 v74, |v73|, v74
	v_exp_f32_e32 v164, v74
	v_add_f32_e32 v74, s0, v72
	v_add_f32_e32 v75, s0, v73
	s_nop 0
	v_cmp_lt_f32_e32 vcc, 0, v74
	s_nop 1
	v_cndmask_b32_e32 v76, v137, v115, vcc
	v_cmp_lt_f32_e32 vcc, 0, v75
	v_mul_f32_e64 v76, |v74|, v76
	v_exp_f32_e32 v76, v76
	v_cndmask_b32_e32 v77, v137, v115, vcc
	v_mul_f32_e64 v77, |v75|, v77
	v_exp_f32_e32 v77, v77
	v_cmp_neq_f32_e32 vcc, 0, v75
	s_nop 1
	v_cndmask_b32_e32 v75, 2.0, v77, vcc
	v_cmp_neq_f32_e32 vcc, 0, v74
	s_nop 1
	v_cndmask_b32_e32 v74, 2.0, v76, vcc
	v_mul_f32_e32 v130, v40, v74
	v_mul_f32_e32 v131, v41, v75
	v_add_f32_e32 v74, s62, v64
	v_add_f32_e32 v75, s63, v64
	v_cmp_lt_f32_e32 vcc, 0, v74
	s_mov_b32 s62, 0xc1c00000
	s_mov_b32 s63, 0xc1c80000
	v_cndmask_b32_e32 v76, v137, v115, vcc
	v_mul_f32_e64 v76, |v74|, v76
	v_cmp_lt_f32_e32 vcc, 0, v75
	v_exp_f32_e32 v165, v76
	s_nop 0
	v_cndmask_b32_e32 v76, v137, v115, vcc
	v_mul_f32_e64 v76, |v75|, v76
	v_exp_f32_e32 v166, v76
	v_add_f32_e32 v76, s0, v74
	v_add_f32_e32 v77, s0, v75
	s_nop 0
	v_cmp_lt_f32_e32 vcc, 0, v76
	s_nop 1
	v_cndmask_b32_e32 v78, v137, v115, vcc
	v_cmp_lt_f32_e32 vcc, 0, v77
	v_mul_f32_e64 v78, |v76|, v78
	v_exp_f32_e32 v78, v78
	v_cndmask_b32_e32 v79, v137, v115, vcc
	v_mul_f32_e64 v79, |v77|, v79
	v_exp_f32_e32 v79, v79
	v_cmp_neq_f32_e32 vcc, 0, v77
	s_nop 1
	v_cndmask_b32_e32 v77, 2.0, v79, vcc
	v_cmp_neq_f32_e32 vcc, 0, v76
	s_nop 1
	v_cndmask_b32_e32 v76, 2.0, v78, vcc
	v_mul_f32_e32 v132, v42, v76
	v_mul_f32_e32 v133, v43, v77
	v_add_f32_e32 v76, s62, v64
	v_add_f32_e32 v77, s63, v64
	v_cmp_lt_f32_e32 vcc, 0, v76
	s_mov_b32 s62, 0xc1d00000
	s_mov_b32 s63, 0xc1d80000
	v_cndmask_b32_e32 v78, v137, v115, vcc
	v_mul_f32_e64 v78, |v76|, v78
	v_cmp_lt_f32_e32 vcc, 0, v77
	v_exp_f32_e32 v167, v78
	s_nop 0
	v_cndmask_b32_e32 v78, v137, v115, vcc
	v_mul_f32_e64 v78, |v77|, v78
	v_exp_f32_e32 v168, v78
	v_add_f32_e32 v78, s0, v76
	v_add_f32_e32 v79, s0, v77
	s_nop 0
	v_cmp_lt_f32_e32 vcc, 0, v78
	s_nop 1
	v_cndmask_b32_e32 v134, v137, v115, vcc
	v_cmp_lt_f32_e32 vcc, 0, v79
	v_mul_f32_e64 v134, |v78|, v134
	v_exp_f32_e32 v134, v134
	v_cndmask_b32_e32 v135, v137, v115, vcc
	v_mul_f32_e64 v135, |v79|, v135
	v_exp_f32_e32 v135, v135
	v_cmp_neq_f32_e32 vcc, 0, v79
	s_nop 1
	v_cndmask_b32_e32 v79, 2.0, v135, vcc
	v_cmp_neq_f32_e32 vcc, 0, v78
	s_nop 1
	v_cndmask_b32_e32 v78, 2.0, v134, vcc
	v_mul_f32_e32 v134, v44, v78
	v_mul_f32_e32 v135, v45, v79
	v_add_f32_e32 v78, s62, v64
	v_add_f32_e32 v79, s63, v64
	v_add_f32_e32 v154, 0xc2000000, v78
	v_cmp_lt_f32_e32 vcc, 0, v78
	s_nop 1
	v_cndmask_b32_e32 v169, v137, v115, vcc
	v_cmp_lt_f32_e32 vcc, 0, v154
	v_mul_f32_e64 v169, |v78|, v169
	v_exp_f32_e32 v169, v169
	v_cndmask_b32_e32 v170, v137, v115, vcc
	v_mul_f32_e64 v170, |v154|, v170
	v_exp_f32_e32 v170, v170
	v_cmp_lt_f32_e32 vcc, 0, v79
	s_nop 1
	v_cndmask_b32_e32 v171, v137, v115, vcc
	v_mul_f32_e64 v171, |v79|, v171
	v_exp_f32_e32 v171, v171
	v_cmp_neq_f32_e32 vcc, 0, v154
	s_nop 1
	v_cndmask_b32_e32 v154, 2.0, v170, vcc
	v_add_f32_e32 v170, 0xc2000000, v79
	v_cmp_lt_f32_e32 vcc, 0, v170
	v_mul_f32_e32 v154, v46, v154
	s_nop 0
	v_cndmask_b32_e32 v172, v137, v115, vcc
	v_cmp_neq_f32_e32 vcc, 0, v79
	v_mul_f32_e64 v172, |v170|, v172
	v_exp_f32_e32 v172, v172
	v_cndmask_b32_e32 v79, 2.0, v171, vcc
	v_cmp_neq_f32_e32 vcc, 0, v78
	s_nop 1
	v_cndmask_b32_e32 v78, 2.0, v169, vcc
	v_cmp_neq_f32_e32 vcc, 0, v77
	s_nop 1
	v_cndmask_b32_e32 v77, 2.0, v168, vcc
	v_cmp_neq_f32_e32 vcc, 0, v76
	s_nop 1
	v_cndmask_b32_e32 v76, 2.0, v167, vcc
	v_cmp_neq_f32_e32 vcc, 0, v75
	s_nop 1
	v_cndmask_b32_e32 v75, 2.0, v166, vcc
	v_cmp_neq_f32_e32 vcc, 0, v74
	s_nop 1
	v_cndmask_b32_e32 v74, 2.0, v165, vcc
	v_cmp_neq_f32_e32 vcc, 0, v73
	s_nop 1
	v_cndmask_b32_e32 v73, 2.0, v164, vcc
	v_cmp_neq_f32_e32 vcc, 0, v72
	s_nop 1
	v_cndmask_b32_e32 v72, 2.0, v163, vcc
	v_cmp_neq_f32_e32 vcc, 0, v71
	s_nop 1
	v_cndmask_b32_e32 v71, 2.0, v162, vcc
	v_cmp_neq_f32_e32 vcc, 0, v70
	s_nop 1
	v_cndmask_b32_e32 v70, 2.0, v161, vcc
	v_cmp_neq_f32_e32 vcc, 0, v69
	s_nop 1
	v_cndmask_b32_e32 v69, 2.0, v160, vcc
	v_cmp_neq_f32_e32 vcc, 0, v68
	s_nop 1
	v_cndmask_b32_e32 v68, 2.0, v159, vcc
	v_cmp_neq_f32_e32 vcc, 0, v67
	s_nop 1
	v_cndmask_b32_e32 v67, 2.0, v158, vcc
	v_cmp_neq_f32_e32 vcc, 0, v66
	s_nop 1
	v_cndmask_b32_e32 v66, 2.0, v157, vcc
	v_cmp_neq_f32_e32 vcc, 0, v64
	s_nop 1
	v_cndmask_b32_e32 v64, 2.0, v155, vcc
	v_cmp_neq_f32_e32 vcc, 0, v65
	s_nop 1
	v_cndmask_b32_e32 v65, 2.0, v156, vcc
	v_cmp_neq_f32_e32 vcc, 0, v170
	s_nop 1
	v_cndmask_b32_e32 v155, 2.0, v172, vcc
	s_cbranch_execz .LBB0_236

.LBB0_240:
	v_cvt_f32_i32_e32 v66, s0
	v_lshl_add_u32 v76, s58, 2, v140
	v_mul_f32_e32 v65, v65, v66
	v_exp_f32_e32 v65, v65
	ds_read_b128 v[66:69], v76 offset:128
	ds_read_b128 v[70:73], v76 offset:160
	v_mul_f32_e32 v156, v64, v65
	s_waitcnt lgkmcnt(1)
	v_mul_f32_e32 v64, v156, v66
	v_mul_f32_e32 v65, v156, v67
	v_mul_f32_e32 v66, v156, v68
	v_mul_f32_e32 v67, v156, v69
	v_mul_f32_e32 v122, v32, v64
	v_mul_f32_e32 v123, v33, v65
	v_mul_f32_e32 v124, v34, v66
	v_mul_f32_e32 v125, v35, v67
	ds_read_b128 v[32:35], v76
	ds_read_b128 v[64:67], v76 offset:32
	s_waitcnt lgkmcnt(2)
	v_mul_f32_e32 v74, v156, v70
	v_mul_f32_e32 v75, v156, v71
	ds_read_b128 v[68:71], v76 offset:192
	v_mul_f32_e32 v126, v36, v74
	v_mul_f32_e32 v127, v37, v75
	v_mul_f32_e32 v36, v156, v72
	v_mul_f32_e32 v37, v156, v73
	v_mul_f32_e32 v128, v38, v36
	v_mul_f32_e32 v129, v39, v37
	ds_read_b128 v[36:39], v76 offset:224
	s_waitcnt lgkmcnt(1)
	v_mul_f32_e32 v68, v156, v68
	v_mul_f32_e32 v69, v156, v69
	v_mul_f32_e32 v130, v40, v68
	v_mul_f32_e32 v131, v41, v69
	v_mul_f32_e32 v40, v156, v70
	v_mul_f32_e32 v41, v156, v71
	v_mul_f32_e32 v132, v42, v40
	v_mul_f32_e32 v133, v43, v41
	ds_read_b128 v[40:43], v76 offset:64
	ds_read_b128 v[68:71], v76 offset:96
	s_waitcnt lgkmcnt(2)
	v_mul_f32_e32 v36, v156, v36
	v_mul_f32_e32 v37, v156, v37
	v_mul_f32_e32 v134, v44, v36
	v_mul_f32_e32 v135, v45, v37
	v_mul_f32_e32 v36, v156, v38
	v_mul_f32_e32 v154, v46, v36
	s_waitcnt lgkmcnt(0)
	v_mul_f32_e32 v78, v156, v70
	v_mul_f32_e32 v79, v156, v71
	v_mul_f32_e32 v74, v156, v42
	v_mul_f32_e32 v75, v156, v43
	v_mul_f32_e32 v70, v156, v66
	v_mul_f32_e32 v71, v156, v67
	v_mul_f32_e32 v66, v156, v34
	v_mul_f32_e32 v67, v156, v35
	v_mul_f32_e32 v76, v156, v68
	v_mul_f32_e32 v77, v156, v69
	v_mul_f32_e32 v72, v156, v40
	v_mul_f32_e32 v73, v156, v41
	v_mul_f32_e32 v68, v156, v64
	v_mul_f32_e32 v69, v156, v65
	v_mul_f32_e32 v64, v156, v32
	v_mul_f32_e32 v65, v156, v33
	v_mul_f32_e32 v155, v156, v39
	s_cmp_ge_u32 s54, s37
	s_cbranch_scc1 .LBB0_231

.LBB0_242:
	s_mul_i32 s37, s60, 0x5000
	s_add_i32 s37, s37, 0
	v_add_u32_e32 v36, s37, v144
	s_waitcnt vmcnt(0)
	s_barrier
	v_add_u32_e32 v32, v36, v151
	ds_read_b128 v[48:51], v32
	ds_read_b128 v[32:35], v32 offset:4096
	v_add_u32_e32 v37, v36, v145
	ds_read_b128 v[64:67], v37
	ds_read_b128 v[52:55], v37 offset:4096
	v_add_u32_e32 v37, v36, v146
	v_add_u32_e32 v36, v36, v147
	ds_read_b128 v[68:71], v37
	ds_read_b128 v[56:59], v37 offset:4096
	ds_read_b128 v[72:75], v36
	ds_read_b128 v[60:63], v36 offset:4096
	s_waitcnt lgkmcnt(6)
	v_mfma_f32_32x32x16_bf16 v[32:47], v[32:35], v[94:97], 0
	s_lshl_b32 s0, s54, 6
	v_add_u32_e32 v130, s33, v116
	s_mov_b32 s1, 0x800000
	s_mov_b32 s72, 0x40c00000
	s_mov_b64 s[66:67], 0x4000
	v_readlane_b32 s73, v254, 13
	s_waitcnt lgkmcnt(4)
	v_mfma_f32_32x32x16_bf16 v[32:47], v[52:55], v[90:93], v[32:47]
	v_add3_u32 v52, s37, v117, v143
	v_add_u32_e32 v131, v52, v142
	ds_read_b64_tr_b16 v[110:111], v131 offset:12288
	ds_read_b64_tr_b16 v[112:113], v131 offset:12800
	ds_read_b64_tr_b16 v[106:107], v131 offset:13312
	ds_read_b64_tr_b16 v[108:109], v131 offset:13824
	ds_read_b64_tr_b16 v[102:103], v131 offset:14336
	ds_read_b64_tr_b16 v[104:105], v131 offset:14848
	ds_read_b64_tr_b16 v[98:99], v131 offset:15360
	ds_read_b64_tr_b16 v[100:101], v131 offset:15872
	s_add_i32 s37, s0, 0xffffff80
	s_addk_i32 s0, 0xffbf
	s_cmp_ge_u32 s0, s33
	s_cselect_b64 s[58:59], -1, 0
	s_waitcnt lgkmcnt(10)
	v_mfma_f32_32x32x16_bf16 v[32:47], v[56:59], v[86:89], v[32:47]
	s_cmp_lt_u32 s0, s33
	s_cselect_b64 s[54:55], -1, 0
	s_cmp_gt_u32 s37, s50
	s_cselect_b64 s[62:63], -1, 0
	s_or_b64 s[54:55], s[54:55], s[62:63]
	s_mov_b64 s[62:63], -1
	s_and_b64 vcc, exec, s[54:55]
	s_waitcnt lgkmcnt(8)
	v_mfma_f32_32x32x16_bf16 v[32:47], v[60:63], v[82:85], v[32:47]
	v_mfma_f32_32x32x16_bf16 v[48:63], v[48:51], v[94:97], 0
	v_mfma_f32_32x32x16_bf16 v[48:63], v[64:67], v[90:93], v[48:63]
	v_mfma_f32_32x32x16_bf16 v[48:63], v[68:71], v[86:89], v[48:63]
	v_mfma_f32_32x32x16_bf16 v[48:63], v[72:75], v[82:85], v[48:63]
	s_cbranch_vccnz .LBB0_244
	v_add_u32_e32 v64, s37, v141
	v_sub_u32_e32 v64, v130, v64
	v_cvt_f32_i32_e32 v64, v64
	s_mov_b32 s0, 0xc2000000
	v_cmp_lt_f32_e32 vcc, 0, v64
	v_add_f32_e32 v65, -1.0, v64
	s_mov_b32 s54, -2.0
	v_cndmask_b32_e32 v66, v137, v115, vcc
	v_mul_f32_e64 v66, |v64|, v66
	v_cmp_lt_f32_e32 vcc, 0, v65
	v_exp_f32_e32 v133, v66
	s_mov_b32 s55, 0xc0400000
	v_cndmask_b32_e32 v66, v137, v115, vcc
	v_mul_f32_e64 v66, |v65|, v66
	v_exp_f32_e32 v134, v66
	v_add_f32_e32 v66, s0, v64
	v_add_f32_e32 v67, s0, v65
	s_mov_b64 s[62:63], 0
	v_cmp_lt_f32_e32 vcc, 0, v66
	s_nop 1
	v_cndmask_b32_e32 v68, v137, v115, vcc
	v_cmp_lt_f32_e32 vcc, 0, v67
	v_mul_f32_e64 v68, |v66|, v68
	v_exp_f32_e32 v68, v68
	v_cndmask_b32_e32 v69, v137, v115, vcc
	v_mul_f32_e64 v69, |v67|, v69
	v_exp_f32_e32 v69, v69
	v_cmp_neq_f32_e32 vcc, 0, v67
	s_nop 1
	v_cndmask_b32_e32 v67, 2.0, v69, vcc
	v_cmp_neq_f32_e32 vcc, 0, v66
	s_nop 1
	v_cndmask_b32_e32 v66, 2.0, v68, vcc
	v_mul_f32_e32 v116, v32, v66
	v_mul_f32_e32 v117, v33, v67
	v_add_f32_e32 v66, s54, v64
	v_add_f32_e32 v67, s55, v64
	v_cmp_lt_f32_e32 vcc, 0, v66
	s_mov_b32 s54, 0xc1000000
	s_mov_b32 s55, 0xc1100000
	v_cndmask_b32_e32 v68, v137, v115, vcc
	v_mul_f32_e64 v68, |v66|, v68
	v_cmp_lt_f32_e32 vcc, 0, v67
	v_exp_f32_e32 v135, v68
	s_nop 0
	v_cndmask_b32_e32 v68, v137, v115, vcc
	v_mul_f32_e64 v68, |v67|, v68
	v_exp_f32_e32 v141, v68
	v_add_f32_e32 v68, s0, v66
	v_add_f32_e32 v69, s0, v67
	s_nop 0
	v_cmp_lt_f32_e32 vcc, 0, v68
	s_nop 1
	v_cndmask_b32_e32 v70, v137, v115, vcc
	v_cmp_lt_f32_e32 vcc, 0, v69
	v_mul_f32_e64 v70, |v68|, v70
	v_exp_f32_e32 v70, v70
	v_cndmask_b32_e32 v71, v137, v115, vcc
	v_mul_f32_e64 v71, |v69|, v71
	v_exp_f32_e32 v71, v71
	v_cmp_neq_f32_e32 vcc, 0, v69
	s_nop 1
	v_cndmask_b32_e32 v69, 2.0, v71, vcc
	v_cmp_neq_f32_e32 vcc, 0, v68
	s_nop 1
	v_cndmask_b32_e32 v68, 2.0, v70, vcc
	v_mul_f32_e32 v118, v34, v68
	v_mul_f32_e32 v119, v35, v69
	v_add_f32_e32 v68, s54, v64
	v_add_f32_e32 v69, s55, v64
	v_cmp_lt_f32_e32 vcc, 0, v68
	s_mov_b32 s54, 0xc1200000
	s_mov_b32 s55, 0xc1300000
	v_cndmask_b32_e32 v70, v137, v115, vcc
	v_mul_f32_e64 v70, |v68|, v70
	v_cmp_lt_f32_e32 vcc, 0, v69
	v_exp_f32_e32 v142, v70
	s_nop 0
	v_cndmask_b32_e32 v70, v137, v115, vcc
	v_mul_f32_e64 v70, |v69|, v70
	v_exp_f32_e32 v143, v70
	v_add_f32_e32 v70, s0, v68
	v_add_f32_e32 v71, s0, v69
	s_nop 0
	v_cmp_lt_f32_e32 vcc, 0, v70
	s_nop 1
	v_cndmask_b32_e32 v72, v137, v115, vcc
	v_cmp_lt_f32_e32 vcc, 0, v71
	v_mul_f32_e64 v72, |v70|, v72
	v_exp_f32_e32 v72, v72
	v_cndmask_b32_e32 v73, v137, v115, vcc
	v_mul_f32_e64 v73, |v71|, v73
	v_exp_f32_e32 v73, v73
	v_cmp_neq_f32_e32 vcc, 0, v71
	s_nop 1
	v_cndmask_b32_e32 v71, 2.0, v73, vcc
	v_cmp_neq_f32_e32 vcc, 0, v70
	s_nop 1
	v_cndmask_b32_e32 v70, 2.0, v72, vcc
	v_mul_f32_e32 v120, v36, v70
	v_mul_f32_e32 v121, v37, v71
	v_add_f32_e32 v70, s54, v64
	v_add_f32_e32 v71, s55, v64
	v_cmp_lt_f32_e32 vcc, 0, v70
	s_mov_b32 s54, 0xc1800000
	s_mov_b32 s55, 0xc1880000
	v_cndmask_b32_e32 v72, v137, v115, vcc
	v_mul_f32_e64 v72, |v70|, v72
	v_cmp_lt_f32_e32 vcc, 0, v71
	v_exp_f32_e32 v144, v72
	s_nop 0
	v_cndmask_b32_e32 v72, v137, v115, vcc
	v_mul_f32_e64 v72, |v71|, v72
	v_exp_f32_e32 v145, v72
	v_add_f32_e32 v72, s0, v70
	v_add_f32_e32 v73, s0, v71
	s_nop 0
	v_cmp_lt_f32_e32 vcc, 0, v72
	s_nop 1
	v_cndmask_b32_e32 v74, v137, v115, vcc
	v_cmp_lt_f32_e32 vcc, 0, v73
	v_mul_f32_e64 v74, |v72|, v74
	v_exp_f32_e32 v74, v74
	v_cndmask_b32_e32 v75, v137, v115, vcc
	v_mul_f32_e64 v75, |v73|, v75
	v_exp_f32_e32 v75, v75
	v_cmp_neq_f32_e32 vcc, 0, v73
	s_nop 1
	v_cndmask_b32_e32 v73, 2.0, v75, vcc
	v_cmp_neq_f32_e32 vcc, 0, v72
	s_nop 1
	v_cndmask_b32_e32 v72, 2.0, v74, vcc
	v_mul_f32_e32 v122, v38, v72
	v_mul_f32_e32 v123, v39, v73
	v_add_f32_e32 v72, s54, v64
	v_add_f32_e32 v73, s55, v64
	v_cmp_lt_f32_e32 vcc, 0, v72
	s_mov_b32 s54, 0xc1900000
	s_mov_b32 s55, 0xc1980000
	v_cndmask_b32_e32 v74, v137, v115, vcc
	v_mul_f32_e64 v74, |v72|, v74
	v_cmp_lt_f32_e32 vcc, 0, v73
	v_exp_f32_e32 v146, v74
	s_nop 0
	v_cndmask_b32_e32 v74, v137, v115, vcc
	v_mul_f32_e64 v74, |v73|, v74
	v_exp_f32_e32 v147, v74
	v_add_f32_e32 v74, s0, v72
	v_add_f32_e32 v75, s0, v73
	s_nop 0
	v_cmp_lt_f32_e32 vcc, 0, v74
	s_nop 1
	v_cndmask_b32_e32 v76, v137, v115, vcc
	v_cmp_lt_f32_e32 vcc, 0, v75
	v_mul_f32_e64 v76, |v74|, v76
	v_exp_f32_e32 v76, v76
	v_cndmask_b32_e32 v77, v137, v115, vcc
	v_mul_f32_e64 v77, |v75|, v77
	v_exp_f32_e32 v77, v77
	v_cmp_neq_f32_e32 vcc, 0, v75
	s_nop 1
	v_cndmask_b32_e32 v75, 2.0, v77, vcc
	v_cmp_neq_f32_e32 vcc, 0, v74
	s_nop 1
	v_cndmask_b32_e32 v74, 2.0, v76, vcc
	v_mul_f32_e32 v124, v40, v74
	v_mul_f32_e32 v125, v41, v75
	v_add_f32_e32 v74, s54, v64
	v_add_f32_e32 v75, s55, v64
	v_cmp_lt_f32_e32 vcc, 0, v74
	s_mov_b32 s54, 0xc1c00000
	s_mov_b32 s55, 0xc1c80000
	v_cndmask_b32_e32 v76, v137, v115, vcc
	v_mul_f32_e64 v76, |v74|, v76
	v_cmp_lt_f32_e32 vcc, 0, v75
	v_exp_f32_e32 v151, v76
	s_nop 0
	v_cndmask_b32_e32 v76, v137, v115, vcc
	v_mul_f32_e64 v76, |v75|, v76
	v_exp_f32_e32 v152, v76
	v_add_f32_e32 v76, s0, v74
	v_add_f32_e32 v77, s0, v75
	s_nop 0
	v_cmp_lt_f32_e32 vcc, 0, v76
	s_nop 1
	v_cndmask_b32_e32 v78, v137, v115, vcc
	v_cmp_lt_f32_e32 vcc, 0, v77
	v_mul_f32_e64 v78, |v76|, v78
	v_exp_f32_e32 v78, v78
	v_cndmask_b32_e32 v79, v137, v115, vcc
	v_mul_f32_e64 v79, |v77|, v79
	v_exp_f32_e32 v79, v79
	v_cmp_neq_f32_e32 vcc, 0, v77
	s_nop 1
	v_cndmask_b32_e32 v77, 2.0, v79, vcc
	v_cmp_neq_f32_e32 vcc, 0, v76
	s_nop 1
	v_cndmask_b32_e32 v76, 2.0, v78, vcc
	v_mul_f32_e32 v126, v42, v76
	v_mul_f32_e32 v127, v43, v77
	v_add_f32_e32 v76, s54, v64
	v_add_f32_e32 v77, s55, v64
	v_cmp_lt_f32_e32 vcc, 0, v76
	s_mov_b32 s54, 0xc1d00000
	s_mov_b32 s55, 0xc1d80000
	v_cndmask_b32_e32 v78, v137, v115, vcc
	v_mul_f32_e64 v78, |v76|, v78
	v_cmp_lt_f32_e32 vcc, 0, v77
	v_exp_f32_e32 v153, v78
	s_nop 0
	v_cndmask_b32_e32 v78, v137, v115, vcc
	v_mul_f32_e64 v78, |v77|, v78
	v_exp_f32_e32 v154, v78
	v_add_f32_e32 v78, s0, v76
	v_add_f32_e32 v79, s0, v77
	s_nop 0
	v_cmp_lt_f32_e32 vcc, 0, v78
	s_nop 1
	v_cndmask_b32_e32 v128, v137, v115, vcc
	v_cmp_lt_f32_e32 vcc, 0, v79
	v_mul_f32_e64 v128, |v78|, v128
	v_exp_f32_e32 v128, v128
	v_cndmask_b32_e32 v129, v137, v115, vcc
	v_mul_f32_e64 v129, |v79|, v129
	v_exp_f32_e32 v129, v129
	v_cmp_neq_f32_e32 vcc, 0, v79
	s_nop 1
	v_cndmask_b32_e32 v79, 2.0, v129, vcc
	v_cmp_neq_f32_e32 vcc, 0, v78
	s_nop 1
	v_cndmask_b32_e32 v78, 2.0, v128, vcc
	v_mul_f32_e32 v128, v44, v78
	v_mul_f32_e32 v129, v45, v79
	v_add_f32_e32 v78, s54, v64
	v_add_f32_e32 v79, s55, v64
	v_add_f32_e32 v132, 0xc2000000, v78
	v_cmp_lt_f32_e32 vcc, 0, v78
	s_nop 1
	v_cndmask_b32_e32 v155, v137, v115, vcc
	v_cmp_lt_f32_e32 vcc, 0, v132
	v_mul_f32_e64 v155, |v78|, v155
	v_exp_f32_e32 v155, v155
	v_cndmask_b32_e32 v156, v137, v115, vcc
	v_mul_f32_e64 v156, |v132|, v156
	v_exp_f32_e32 v156, v156
	v_cmp_lt_f32_e32 vcc, 0, v79
	s_nop 1
	v_cndmask_b32_e32 v157, v137, v115, vcc
	v_mul_f32_e64 v157, |v79|, v157
	v_exp_f32_e32 v157, v157
	v_cmp_neq_f32_e32 vcc, 0, v132
	s_nop 1
	v_cndmask_b32_e32 v132, 2.0, v156, vcc
	v_add_f32_e32 v156, 0xc2000000, v79
	v_cmp_lt_f32_e32 vcc, 0, v156
	v_mul_f32_e32 v132, v46, v132
	s_nop 0
	v_cndmask_b32_e32 v158, v137, v115, vcc
	v_cmp_neq_f32_e32 vcc, 0, v79
	v_mul_f32_e64 v158, |v156|, v158
	v_exp_f32_e32 v158, v158
	v_cndmask_b32_e32 v79, 2.0, v157, vcc
	v_cmp_neq_f32_e32 vcc, 0, v78
	s_nop 1
	v_cndmask_b32_e32 v78, 2.0, v155, vcc
	v_cmp_neq_f32_e32 vcc, 0, v77
	s_nop 1
	v_cndmask_b32_e32 v77, 2.0, v154, vcc
	v_cmp_neq_f32_e32 vcc, 0, v76
	s_nop 1
	v_cndmask_b32_e32 v76, 2.0, v153, vcc
	v_cmp_neq_f32_e32 vcc, 0, v75
	s_nop 1
	v_cndmask_b32_e32 v75, 2.0, v152, vcc
	v_cmp_neq_f32_e32 vcc, 0, v74
	s_nop 1
	v_cndmask_b32_e32 v74, 2.0, v151, vcc
	v_cmp_neq_f32_e32 vcc, 0, v73
	s_nop 1
	v_cndmask_b32_e32 v73, 2.0, v147, vcc
	v_cmp_neq_f32_e32 vcc, 0, v72
	s_nop 1
	v_cndmask_b32_e32 v72, 2.0, v146, vcc
	v_cmp_neq_f32_e32 vcc, 0, v71
	s_nop 1
	v_cndmask_b32_e32 v71, 2.0, v145, vcc
	v_cmp_neq_f32_e32 vcc, 0, v70
	s_nop 1
	v_cndmask_b32_e32 v70, 2.0, v144, vcc
	v_cmp_neq_f32_e32 vcc, 0, v69
	s_nop 1
	v_cndmask_b32_e32 v69, 2.0, v143, vcc
	v_cmp_neq_f32_e32 vcc, 0, v68
	s_nop 1
	v_cndmask_b32_e32 v68, 2.0, v142, vcc
	v_cmp_neq_f32_e32 vcc, 0, v67
	s_nop 1
	v_cndmask_b32_e32 v67, 2.0, v141, vcc
	v_cmp_neq_f32_e32 vcc, 0, v66
	s_nop 1
	v_cndmask_b32_e32 v66, 2.0, v135, vcc
	v_cmp_neq_f32_e32 vcc, 0, v64
	s_nop 1
	v_cndmask_b32_e32 v64, 2.0, v133, vcc
	v_cmp_neq_f32_e32 vcc, 0, v65
	s_nop 1
	v_cndmask_b32_e32 v65, 2.0, v134, vcc
	v_cmp_neq_f32_e32 vcc, 0, v156
	s_nop 1
	v_cndmask_b32_e32 v133, 2.0, v158, vcc

.LBB0_249:
	v_cvt_f32_i32_e32 v65, s0
	v_lshl_add_u32 v76, s33, 2, v140
	v_mul_f32_e32 v64, v64, v65
	v_exp_f32_e32 v72, v64
	ds_read_b128 v[64:67], v76 offset:128
	ds_read_b128 v[68:71], v76 offset:160
	v_mul_f32_e32 v134, v138, v72
	s_waitcnt lgkmcnt(1)
	v_mul_f32_e32 v64, v134, v64
	v_mul_f32_e32 v65, v134, v65
	v_mul_f32_e32 v66, v134, v66
	v_mul_f32_e32 v67, v134, v67
	v_mul_f32_e32 v116, v32, v64
	v_mul_f32_e32 v117, v33, v65
	v_mul_f32_e32 v118, v34, v66
	v_mul_f32_e32 v119, v35, v67
	ds_read_b128 v[32:35], v76
	ds_read_b128 v[64:67], v76 offset:32
	ds_read_b128 v[72:75], v76 offset:192
	s_waitcnt lgkmcnt(3)
	v_mul_f32_e32 v68, v134, v68
	v_mul_f32_e32 v69, v134, v69
	v_mul_f32_e32 v120, v36, v68
	v_mul_f32_e32 v121, v37, v69
	v_mul_f32_e32 v36, v134, v70
	v_mul_f32_e32 v37, v134, v71
	v_mul_f32_e32 v122, v38, v36
	v_mul_f32_e32 v123, v39, v37
	ds_read_b128 v[36:39], v76 offset:224
	s_waitcnt lgkmcnt(1)
	v_mul_f32_e32 v68, v134, v72
	v_mul_f32_e32 v69, v134, v73
	v_mul_f32_e32 v124, v40, v68
	v_mul_f32_e32 v125, v41, v69
	v_mul_f32_e32 v40, v134, v74
	v_mul_f32_e32 v41, v134, v75
	v_mul_f32_e32 v126, v42, v40
	v_mul_f32_e32 v127, v43, v41
	ds_read_b128 v[40:43], v76 offset:64
	ds_read_b128 v[68:71], v76 offset:96
	s_waitcnt lgkmcnt(2)
	v_mul_f32_e32 v36, v134, v36
	v_mul_f32_e32 v37, v134, v37
	v_mul_f32_e32 v128, v44, v36
	v_mul_f32_e32 v129, v45, v37
	v_mul_f32_e32 v36, v134, v38
	v_mul_f32_e32 v132, v46, v36
	s_waitcnt lgkmcnt(0)
	v_mul_f32_e32 v78, v134, v70
	v_mul_f32_e32 v79, v134, v71
	v_mul_f32_e32 v74, v134, v42
	v_mul_f32_e32 v75, v134, v43
	v_mul_f32_e32 v70, v134, v66
	v_mul_f32_e32 v71, v134, v67
	v_mul_f32_e32 v66, v134, v34
	v_mul_f32_e32 v67, v134, v35
	v_mul_f32_e32 v76, v134, v68
	v_mul_f32_e32 v77, v134, v69
	v_mul_f32_e32 v72, v134, v40
	v_mul_f32_e32 v73, v134, v41
	v_mul_f32_e32 v68, v134, v64
	v_mul_f32_e32 v69, v134, v65
	v_mul_f32_e32 v64, v134, v32
	v_mul_f32_e32 v65, v134, v33
	v_mul_f32_e32 v133, v134, v39
.LBB0_250:
	s_nop 8
	v_mul_f32_e32 v36, v54, v70
	v_mul_f32_e32 v37, v55, v71
	v_mul_f32_e32 v34, v52, v68
	v_mul_f32_e32 v35, v53, v69
	v_mul_f32_e32 v38, v50, v66
	v_mul_f32_e32 v39, v51, v67
	v_mul_f32_e32 v32, v48, v64
	v_mul_f32_e32 v33, v49, v65
	v_cvt_pk_bf16_f32 v34, v34, v35
	v_cvt_pk_bf16_f32 v32, v32, v33
	v_cvt_pk_bf16_f32 v33, v38, v39
	v_cvt_pk_bf16_f32 v35, v36, v37
	ds_read_b64_tr_b16 v[48:49], v131 offset:16384
	ds_read_b64_tr_b16 v[50:51], v131 offset:16896
	ds_read_b64_tr_b16 v[52:53], v131 offset:17408
	ds_read_b64_tr_b16 v[54:55], v131 offset:17920
	s_waitcnt lgkmcnt(10)
	v_mfma_f32_32x32x16_bf16 v[16:31], v[32:35], v[110:113], v[16:31]
	v_mul_f32_e64 v40, v62, v78
	v_mul_f32_e64 v41, v63, v79
	v_mul_f32_e64 v38, v60, v76
	v_mul_f32_e64 v39, v61, v77
	v_mul_f32_e64 v42, v58, v74
	v_mul_f32_e64 v43, v59, v75
	v_mul_f32_e32 v36, v56, v72
	v_mul_f32_e32 v37, v57, v73
	v_cvt_pk_bf16_f32 v38, v38, v39
	v_cvt_pk_bf16_f32 v36, v36, v37
	v_cvt_pk_bf16_f32 v37, v42, v43
	s_waitcnt lgkmcnt(2)
	v_mfma_f32_32x32x16_bf16 v[0:15], v[32:35], v[48:51], v[0:15]
	v_cvt_pk_bf16_f32 v39, v40, v41
	v_cvt_pk_bf16_f32 v40, v116, v117
	v_cvt_pk_bf16_f32 v41, v118, v119
	v_cvt_pk_bf16_f32 v42, v120, v121
	v_cvt_pk_bf16_f32 v43, v122, v123
	v_mul_f32_e32 v47, v47, v133
	v_cvt_pk_bf16_f32 v44, v124, v125
	v_mfma_f32_32x32x16_bf16 v[16:31], v[36:39], v[106:109], v[16:31]
	v_cvt_pk_bf16_f32 v45, v126, v127
	v_cvt_pk_bf16_f32 v46, v128, v129
	v_cvt_pk_bf16_f32 v47, v132, v47
	s_cmp_lg_u64 s[52:53], 0
	s_waitcnt lgkmcnt(0)
	v_mfma_f32_32x32x16_bf16 v[0:15], v[36:39], v[52:55], v[0:15]
	ds_read_b64_tr_b16 v[32:33], v131 offset:18432
	ds_read_b64_tr_b16 v[34:35], v131 offset:18944
	ds_read_b64_tr_b16 v[36:37], v131 offset:19456
	ds_read_b64_tr_b16 v[38:39], v131 offset:19968
	v_mfma_f32_32x32x16_bf16 v[16:31], v[40:43], v[102:105], v[16:31]
	s_waitcnt lgkmcnt(2)
	v_mfma_f32_32x32x16_bf16 v[0:15], v[40:43], v[32:35], v[0:15]
	v_mfma_f32_32x32x16_bf16 v[16:31], v[44:47], v[98:101], v[16:31]
	s_waitcnt lgkmcnt(0)
	v_mfma_f32_32x32x16_bf16 v[0:15], v[44:47], v[36:39], v[0:15]
	s_cbranch_scc0 .LBB0_252
	v_add_u32_e32 v32, 1, v130
	v_cvt_f32_i32_e32 v32, v32
	v_lshlrev_b32_e32 v34, 16, v94
	v_and_b32_e32 v35, 0xffff0000, v94
	v_lshlrev_b32_e32 v40, 16, v97
	v_mul_f32_e32 v32, v115, v32
	v_exp_f32_e32 v46, v32
	v_sub_u32_e32 v32, s3, v130
	v_cvt_f32_i32_e32 v32, v32
	v_ashrrev_i32_e32 v115, 31, v114
	v_and_b32_e32 v41, 0xffff0000, v97
	v_lshlrev_b64 v[60:61], 7, v[114:115]
	v_mul_f32_e32 v32, v137, v32
	v_exp_f32_e32 v48, v32
	v_lshlrev_b32_e32 v32, 3, v136
	v_ashrrev_i32_e32 v33, 31, v32
	v_lshlrev_b64 v[32:33], 1, v[32:33]
	v_lshl_add_u64 v[56:57], s[52:53], 0, v[32:33]
	v_lshl_add_u64 v[58:59], s[56:57], 0, v[32:33]
	v_mul_f32_e32 v32, v46, v34
	v_mul_f32_e32 v33, v46, v35
	v_mul_f32_e32 v34, v48, v34
	v_mul_f32_e32 v35, v48, v35
	v_cvt_pk_bf16_f32 v36, v34, v35
	v_lshlrev_b32_e32 v34, 16, v95
	v_and_b32_e32 v35, 0xffff0000, v95
	v_mul_f32_e32 v38, v46, v34
	v_mul_f32_e32 v39, v46, v35
	v_cvt_pk_bf16_f32 v32, v32, v33
	v_cvt_pk_bf16_f32 v33, v38, v39
	v_mul_f32_e32 v34, v48, v34
	v_mul_f32_e32 v35, v48, v35
	v_lshlrev_b32_e32 v38, 16, v96
	v_and_b32_e32 v39, 0xffff0000, v96
	v_cvt_pk_bf16_f32 v37, v34, v35
	v_mul_f32_e32 v34, v46, v38
	v_mul_f32_e32 v35, v46, v39
	v_mul_f32_e32 v38, v48, v38
	v_mul_f32_e32 v39, v48, v39
	v_mul_f32_e32 v42, v46, v40
	v_mul_f32_e32 v43, v46, v41
	v_mul_f32_e32 v40, v48, v40
	v_mul_f32_e32 v41, v48, v41
	v_lshl_add_u64 v[50:51], v[56:57], 0, v[60:61]
	v_cvt_pk_bf16_f32 v34, v34, v35
	v_cvt_pk_bf16_f32 v38, v38, v39
	v_cvt_pk_bf16_f32 v35, v42, v43
	v_cvt_pk_bf16_f32 v39, v40, v41
	global_load_dwordx4 v[40:43], v[50:51], off
	v_lshl_add_u64 v[44:45], v[58:59], 0, v[60:61]
	global_load_dwordx4 v[52:55], v[44:45], off
	s_waitcnt vmcnt(0) lgkmcnt(0)
	v_mfma_f32_32x32x16_bf16 v[16:31], v[32:35], v[40:43], v[16:31]
	v_lshl_add_u64 v[40:41], v[60:61], 0, s[82:83]
	v_lshl_add_u64 v[42:43], v[56:57], 0, v[40:41]
	v_lshl_add_u64 v[40:41], v[58:59], 0, v[40:41]
	global_load_dwordx4 v[56:59], v[40:41], off
	v_mfma_f32_32x32x16_bf16 v[16:31], v[36:39], v[52:55], v[16:31]
	global_load_dwordx4 v[52:55], v[42:43], off
	s_waitcnt vmcnt(0) lgkmcnt(0)
	v_mfma_f32_32x32x16_bf16 v[0:15], v[32:35], v[52:55], v[0:15]
	v_lshlrev_b32_e32 v34, 16, v90
	v_and_b32_e32 v35, 0xffff0000, v90
	v_mul_f32_e64 v32, v46, v34
	v_mul_f32_e64 v33, v46, v35
	v_mul_f32_e64 v34, v48, v34
	v_mul_f32_e64 v35, v48, v35
	v_cvt_pk_bf16_f32 v32, v32, v33
	v_lshlrev_b32_e32 v52, 16, v93
	v_and_b32_e32 v53, 0xffff0000, v93
	v_mfma_f32_32x32x16_bf16 v[0:15], v[36:39], v[56:59], v[0:15]
	v_cvt_pk_bf16_f32 v36, v34, v35
	v_lshlrev_b32_e32 v34, 16, v91
	v_and_b32_e32 v35, 0xffff0000, v91
	v_mul_f32_e64 v38, v46, v34
	v_mul_f32_e64 v39, v46, v35
	v_cvt_pk_bf16_f32 v33, v38, v39
	v_mul_f32_e32 v34, v48, v34
	v_mul_f32_e32 v35, v48, v35
	v_lshlrev_b32_e32 v38, 16, v92
	v_and_b32_e32 v39, 0xffff0000, v92
	v_cvt_pk_bf16_f32 v37, v34, v35
	v_mul_f32_e32 v34, v46, v38
	v_mul_f32_e32 v35, v46, v39
	v_mul_f32_e32 v38, v48, v38
	v_mul_f32_e32 v39, v48, v39
	v_mul_f32_e32 v54, v46, v52
	v_mul_f32_e32 v55, v46, v53
	v_mul_f32_e32 v52, v48, v52
	v_mul_f32_e32 v53, v48, v53
	v_cvt_pk_bf16_f32 v34, v34, v35
	v_cvt_pk_bf16_f32 v38, v38, v39
	v_cvt_pk_bf16_f32 v35, v54, v55
	v_cvt_pk_bf16_f32 v39, v52, v53
	global_load_dwordx4 v[52:55], v[50:51], off offset:32
	global_load_dwordx4 v[56:59], v[44:45], off offset:32
	s_waitcnt vmcnt(0) lgkmcnt(0)
	v_mfma_f32_32x32x16_bf16 v[16:31], v[32:35], v[52:55], v[16:31]
	v_mfma_f32_32x32x16_bf16 v[16:31], v[36:39], v[56:59], v[16:31]
	global_load_dwordx4 v[52:55], v[42:43], off offset:32
	global_load_dwordx4 v[56:59], v[40:41], off offset:32
	s_waitcnt vmcnt(0) lgkmcnt(0)
	v_mfma_f32_32x32x16_bf16 v[0:15], v[32:35], v[52:55], v[0:15]
	v_lshlrev_b32_e32 v34, 16, v86
	v_and_b32_e32 v35, 0xffff0000, v86
	v_mul_f32_e64 v32, v46, v34
	v_mul_f32_e64 v33, v46, v35
	v_mul_f32_e64 v34, v48, v34
	v_mul_f32_e64 v35, v48, v35
	v_cvt_pk_bf16_f32 v32, v32, v33
	v_lshlrev_b32_e32 v52, 16, v89
	v_and_b32_e32 v53, 0xffff0000, v89
	v_mfma_f32_32x32x16_bf16 v[0:15], v[36:39], v[56:59], v[0:15]
	v_cvt_pk_bf16_f32 v36, v34, v35
	v_lshlrev_b32_e32 v34, 16, v87
	v_and_b32_e32 v35, 0xffff0000, v87
	v_mul_f32_e64 v38, v46, v34
	v_mul_f32_e64 v39, v46, v35
	v_cvt_pk_bf16_f32 v33, v38, v39
	v_mul_f32_e32 v34, v48, v34
	v_mul_f32_e32 v35, v48, v35
	v_lshlrev_b32_e32 v38, 16, v88
	v_and_b32_e32 v39, 0xffff0000, v88
	v_cvt_pk_bf16_f32 v37, v34, v35
	v_mul_f32_e32 v34, v46, v38
	v_mul_f32_e32 v35, v46, v39
	v_mul_f32_e32 v38, v48, v38
	v_mul_f32_e32 v39, v48, v39
	v_mul_f32_e32 v54, v46, v52
	v_mul_f32_e32 v55, v46, v53
	v_mul_f32_e32 v52, v48, v52
	v_mul_f32_e32 v53, v48, v53
	v_cvt_pk_bf16_f32 v34, v34, v35
	v_cvt_pk_bf16_f32 v38, v38, v39
	v_cvt_pk_bf16_f32 v35, v54, v55
	v_cvt_pk_bf16_f32 v39, v52, v53
	global_load_dwordx4 v[52:55], v[50:51], off offset:64
	global_load_dwordx4 v[56:59], v[44:45], off offset:64
	s_waitcnt vmcnt(0) lgkmcnt(0)
	v_mfma_f32_32x32x16_bf16 v[16:31], v[32:35], v[52:55], v[16:31]
	v_mfma_f32_32x32x16_bf16 v[16:31], v[36:39], v[56:59], v[16:31]
	global_load_dwordx4 v[52:55], v[42:43], off offset:64
	global_load_dwordx4 v[56:59], v[40:41], off offset:64
	s_waitcnt vmcnt(0) lgkmcnt(0)
	v_mfma_f32_32x32x16_bf16 v[0:15], v[32:35], v[52:55], v[0:15]
	v_lshlrev_b32_e32 v32, 16, v82
	v_and_b32_e32 v33, 0xffff0000, v82
	v_mul_f32_e64 v34, v46, v32
	v_mul_f32_e64 v35, v46, v33
	v_mul_f32_e64 v32, v48, v32
	v_mul_f32_e64 v33, v48, v33
	v_cvt_pk_bf16_f32 v32, v32, v33
	v_lshlrev_b32_e32 v52, 16, v85
	v_and_b32_e32 v53, 0xffff0000, v85
	v_mfma_f32_32x32x16_bf16 v[0:15], v[36:39], v[56:59], v[0:15]
	v_cvt_pk_bf16_f32 v36, v34, v35
	v_lshlrev_b32_e32 v34, 16, v83
	v_and_b32_e32 v35, 0xffff0000, v83
	v_mul_f32_e64 v38, v46, v34
	v_mul_f32_e64 v39, v46, v35
	v_mul_f32_e32 v34, v48, v34
	v_mul_f32_e32 v35, v48, v35
	v_cvt_pk_bf16_f32 v33, v34, v35
	v_lshlrev_b32_e32 v34, 16, v84
	v_and_b32_e32 v35, 0xffff0000, v84
	v_cvt_pk_bf16_f32 v37, v38, v39
	v_mul_f32_e32 v38, v46, v34
	v_mul_f32_e32 v39, v46, v35
	v_mul_f32_e32 v47, v46, v53
	v_mul_f32_e32 v46, v46, v52
	v_cvt_pk_bf16_f32 v38, v38, v39
	v_mul_f32_e32 v34, v48, v34
	v_mul_f32_e32 v35, v48, v35
	v_cvt_pk_bf16_f32 v39, v46, v47
	v_mul_f32_e32 v46, v48, v52
	v_mul_f32_e32 v47, v48, v53
	v_cvt_pk_bf16_f32 v34, v34, v35
	v_cvt_pk_bf16_f32 v35, v46, v47
	global_load_dwordx4 v[46:49], v[50:51], off offset:96
	s_nop 0
	global_load_dwordx4 v[50:53], v[44:45], off offset:96
	s_waitcnt vmcnt(0) lgkmcnt(0)
	v_mfma_f32_32x32x16_bf16 v[16:31], v[36:39], v[46:49], v[16:31]
	global_load_dwordx4 v[42:45], v[42:43], off offset:96
	s_nop 0
	global_load_dwordx4 v[46:49], v[40:41], off offset:96
	v_mfma_f32_32x32x16_bf16 v[16:31], v[32:35], v[50:53], v[16:31]
	s_waitcnt vmcnt(0) lgkmcnt(0)
	v_mfma_f32_32x32x16_bf16 v[0:15], v[36:39], v[42:45], v[0:15]
	v_mfma_f32_32x32x16_bf16 v[0:15], v[32:35], v[46:49], v[0:15]

.LBB0_264:
	s_or_b64 exec, exec, s[56:57]
	s_lshl_b64 s[36:37], s[52:53], 2
	s_add_u32 s64, s39, s36
	s_addc_u32 s65, s8, s37
	v_ashrrev_i32_e32 v56, 3, v80
	s_add_i32 s0, s40, s51
	s_lshl_b32 s60, s2, 1
	v_lshlrev_b32_e32 v33, 3, v80
	v_add_u32_e32 v32, s0, v56
	s_add_u32 s2, s18, s60
	v_and_b32_e32 v57, 56, v33
	s_addc_u32 s3, s19, 0
	v_lshlrev_b32_e32 v80, 1, v57
	v_ashrrev_i32_e32 v33, 31, v32
	v_add_u32_e32 v38, 8, v32
	v_lshl_add_u64 v[34:35], s[2:3], 0, v[80:81]
	v_lshlrev_b64 v[52:53], 11, v[32:33]
	v_ashrrev_i32_e32 v39, 31, v38
	v_lshl_add_u64 v[36:37], v[34:35], 0, v[52:53]
	v_lshlrev_b64 v[54:55], 11, v[38:39]
	s_waitcnt lgkmcnt(0)
	s_barrier
	v_lshl_add_u64 v[38:39], v[34:35], 0, v[54:55]
	global_load_dwordx4 v[40:43], v[36:37], off
	global_load_dwordx4 v[44:47], v[38:39], off
	v_add_u32_e32 v36, 16, v32
	v_add_u32_e32 v32, 24, v32
	v_ashrrev_i32_e32 v37, 31, v36
	v_ashrrev_i32_e32 v33, 31, v32
	s_movk_i32 s0, 0x440
	v_lshlrev_b64 v[38:39], 11, v[36:37]
	v_lshlrev_b64 v[36:37], 11, v[32:33]
	v_lshlrev_b32_e32 v58, 2, v114
	v_mul_lo_u32 v59, v136, s0
	v_lshl_add_u64 v[48:49], v[34:35], 0, v[38:39]
	v_lshl_add_u64 v[32:33], v[34:35], 0, v[36:37]
	v_add3_u32 v58, s9, v58, v59
	global_load_dwordx4 v[48:51], v[48:49], off
	s_nop 0
	global_load_dwordx4 v[32:35], v[32:33], off
	ds_write2_b32 v58, v16, v0 offset1:32
	ds_write2_b32 v58, v17, v1 offset0:68 offset1:100
	ds_write2_b32 v58, v18, v2 offset0:136 offset1:168
	ds_write2_b32 v58, v19, v3 offset0:204 offset1:236
	v_add_u32_e32 v0, 0x800, v58
	ds_write2_b32 v0, v20, v4 offset0:32 offset1:64
	ds_write2_b32 v0, v21, v5 offset0:100 offset1:132
	ds_write2_b32 v0, v22, v6 offset0:168 offset1:200
	v_add_u32_e32 v0, 0xa00, v58
	ds_write2_b32 v0, v23, v7 offset0:108 offset1:140
	v_add_u32_e32 v0, 0x1000, v58
	ds_write2_b32 v0, v24, v8 offset0:64 offset1:96
	ds_write2_b32 v0, v25, v9 offset0:132 offset1:164
	ds_write2_b32 v0, v26, v10 offset0:200 offset1:232
	v_add_u32_e32 v0, 0x1400, v58
	ds_write2_b32 v0, v27, v11 offset0:12 offset1:44
	v_add_u32_e32 v0, 0x1800, v58
	ds_write2_b32 v0, v28, v12 offset0:96 offset1:128
	ds_write2_b32 v0, v29, v13 offset0:164 offset1:196
	v_add_u32_e32 v0, 0x1a00, v58
	ds_write2_b32 v0, v30, v14 offset0:104 offset1:136
	v_add_u32_e32 v0, 0x1c00, v58
	ds_write2_b32 v0, v31, v15 offset0:44 offset1:76
	v_lshlrev_b32_e32 v0, 2, v57
	v_mul_lo_u32 v1, v56, s77
	v_add3_u32 v16, s9, v0, v1
	s_waitcnt lgkmcnt(0)
	ds_read_b128 v[0:3], v16
	ds_read_b128 v[4:7], v16 offset:16
	s_mov_b64 s[40:41], s[42:43]
	s_waitcnt lgkmcnt(0)
	v_mul_f32_e32 v8, v2, v2
	v_mul_f32_e32 v9, v3, v3
	v_mul_f32_e32 v10, v0, v0
	v_mul_f32_e32 v11, v1, v1
	s_nop 0
	v_pk_mov_b32 v[12:13], v[10:11], v[8:9] op_sel:[1,0]
	v_mov_b32_e32 v11, v9
	v_add_f32_e32 v8, v12, v10
	v_add_f32_e32 v9, v13, v11
	v_mul_f32_e32 v10, v6, v6
	v_mul_f32_e32 v11, v7, v7
	v_mul_f32_e32 v12, v4, v4
	v_mul_f32_e32 v13, v5, v5
	v_mov_b32_e32 v14, v10
	v_mov_b32_e32 v15, v12
	v_mov_b32_e32 v12, v11
	v_add_f32_e32 v10, v14, v12
	v_add_f32_e32 v11, v15, v13
	v_add_f32_e32 v8, v8, v9
	v_add_f32_e32 v8, v8, v11
	v_add_f32_e32 v8, v10, v8
	s_nop 1
	v_add_f32_dpp v8, v8, v8 quad_perm:[1,0,3,2] row_mask:0xf bank_mask:0xf
	s_nop 1
	v_add_f32_dpp v8, v8, v8 quad_perm:[2,3,0,1] row_mask:0xf bank_mask:0xf
	s_nop 1
	v_add_f32_dpp v8, v8, v8 row_half_mirror row_mask:0xf bank_mask:0xf
	v_fmamk_f32 v8, v8, 0x3c800000, v180
	v_mul_f32_e32 v9, 0x4b800000, v8
	v_cmp_gt_f32_e32 vcc, s1, v8
	s_waitcnt vmcnt(0)
	v_lshlrev_b32_e32 v10, 16, v40
	v_cndmask_b32_e32 v8, v8, v9, vcc
	v_rsq_f32_e32 v8, v8
	v_and_b32_e32 v11, 0xffff0000, v40
	v_mul_f32_e32 v9, 0x45800000, v8
	v_cndmask_b32_e32 v8, v8, v9, vcc
	v_mul_f32_e32 v0, v0, v8
	v_mul_f32_e32 v1, v1, v8
	v_mul_f32_e32 v2, v2, v8
	v_mul_f32_e32 v3, v3, v8
	v_mul_f32_e32 v0, v0, v10
	v_mul_f32_e32 v1, v1, v11
	v_lshlrev_b32_e32 v10, 16, v41
	v_and_b32_e32 v11, 0xffff0000, v41
	v_mul_f32_e32 v2, v2, v10
	v_mul_f32_e32 v3, v3, v11
	v_cvt_pk_bf16_f32 v0, v0, v1
	v_cvt_pk_bf16_f32 v1, v2, v3
	v_mul_f32_e32 v2, v4, v8
	v_mul_f32_e32 v3, v5, v8
	v_lshlrev_b32_e32 v4, 16, v42
	v_and_b32_e32 v5, 0xffff0000, v42
	v_mul_f32_e32 v2, v2, v4
	v_mul_f32_e32 v3, v3, v5
	v_mul_f32_e32 v4, v6, v8
	v_mul_f32_e32 v5, v7, v8
	v_lshlrev_b32_e32 v6, 16, v43
	v_and_b32_e32 v7, 0xffff0000, v43
	v_mul_f32_e32 v4, v4, v6
	v_mul_f32_e32 v5, v5, v7
	v_cvt_pk_bf16_f32 v2, v2, v3
	v_cvt_pk_bf16_f32 v3, v4, v5
	v_lshl_add_u64 v[4:5], s[26:27], 0, v[52:53]
	v_lshl_add_u64 v[4:5], v[4:5], 0, s[60:61]
	v_lshl_add_u64 v[4:5], v[4:5], 0, v[80:81]
	global_store_dwordx4 v[4:5], v[0:3], off sc1
	s_nop 1
	ds_read_b128 v[0:3], v16 offset:2176
	ds_read_b128 v[4:7], v16 offset:2192
	s_waitcnt lgkmcnt(1)
	v_mul_f32_e32 v8, v2, v2
	v_mul_f32_e32 v9, v3, v3
	v_mul_f32_e32 v10, v0, v0
	v_mul_f32_e32 v11, v1, v1
	s_nop 0
	v_pk_mov_b32 v[12:13], v[10:11], v[8:9] op_sel:[1,0]
	v_mov_b32_e32 v11, v9
	v_add_f32_e32 v8, v12, v10
	v_add_f32_e32 v9, v13, v11
	s_waitcnt lgkmcnt(0)
	v_mul_f32_e32 v10, v6, v6
	v_mul_f32_e32 v11, v7, v7
	v_mul_f32_e32 v12, v4, v4
	v_mul_f32_e32 v13, v5, v5
	v_mov_b32_e32 v14, v10
	v_mov_b32_e32 v15, v12
	v_mov_b32_e32 v12, v11
	v_add_f32_e32 v10, v14, v12
	v_add_f32_e32 v11, v15, v13
	v_add_f32_e32 v8, v8, v9
	v_add_f32_e32 v8, v8, v11
	v_add_f32_e32 v8, v10, v8
	v_lshlrev_b32_e32 v10, 16, v44
	v_and_b32_e32 v11, 0xffff0000, v44
	s_nop 1
	v_add_f32_dpp v8, v8, v8 quad_perm:[1,0,3,2] row_mask:0xf bank_mask:0xf
	s_nop 1
	v_add_f32_dpp v8, v8, v8 quad_perm:[2,3,0,1] row_mask:0xf bank_mask:0xf
	s_nop 1
	v_add_f32_dpp v8, v8, v8 row_half_mirror row_mask:0xf bank_mask:0xf
	v_fmamk_f32 v8, v8, 0x3c800000, v180
	v_mul_f32_e32 v9, 0x4b800000, v8
	v_cmp_gt_f32_e32 vcc, s1, v8
	s_nop 1
	v_cndmask_b32_e32 v8, v8, v9, vcc
	v_rsq_f32_e32 v8, v8
	s_nop 0
	v_mul_f32_e32 v9, 0x45800000, v8
	v_cndmask_b32_e32 v8, v8, v9, vcc
	v_mul_f32_e32 v0, v0, v8
	v_mul_f32_e32 v1, v1, v8
	v_mul_f32_e32 v2, v2, v8
	v_mul_f32_e32 v3, v3, v8
	v_mul_f32_e32 v0, v0, v10
	v_mul_f32_e32 v1, v1, v11
	v_lshlrev_b32_e32 v10, 16, v45
	v_and_b32_e32 v11, 0xffff0000, v45
	v_mul_f32_e32 v2, v2, v10
	v_mul_f32_e32 v3, v3, v11
	v_cvt_pk_bf16_f32 v0, v0, v1
	v_cvt_pk_bf16_f32 v1, v2, v3
	v_mul_f32_e32 v2, v4, v8
	v_mul_f32_e32 v3, v5, v8
	v_lshlrev_b32_e32 v4, 16, v46
	v_and_b32_e32 v5, 0xffff0000, v46
	v_mul_f32_e32 v2, v2, v4
	v_mul_f32_e32 v3, v3, v5
	v_mul_f32_e32 v4, v6, v8
	v_mul_f32_e32 v5, v7, v8
	v_lshlrev_b32_e32 v6, 16, v47
	v_and_b32_e32 v7, 0xffff0000, v47
	v_mul_f32_e32 v4, v4, v6
	v_mul_f32_e32 v5, v5, v7
	v_cvt_pk_bf16_f32 v2, v2, v3
	v_cvt_pk_bf16_f32 v3, v4, v5
	v_lshl_add_u64 v[4:5], s[26:27], 0, v[54:55]
	v_lshl_add_u64 v[4:5], v[4:5], 0, s[60:61]
	v_lshl_add_u64 v[4:5], v[4:5], 0, v[80:81]
	global_store_dwordx4 v[4:5], v[0:3], off sc1
	s_nop 1
	ds_read_b128 v[0:3], v16 offset:4352
	ds_read_b128 v[4:7], v16 offset:4368
	s_waitcnt lgkmcnt(1)
	v_mul_f32_e32 v8, v2, v2
	v_mul_f32_e32 v9, v3, v3
	v_mul_f32_e32 v10, v0, v0
	v_mul_f32_e32 v11, v1, v1
	s_nop 0
	v_pk_mov_b32 v[12:13], v[10:11], v[8:9] op_sel:[1,0]
	v_mov_b32_e32 v11, v9
	v_add_f32_e32 v8, v12, v10
	v_add_f32_e32 v9, v13, v11
	s_waitcnt lgkmcnt(0)
	v_mul_f32_e32 v10, v6, v6
	v_mul_f32_e32 v11, v7, v7
	v_mul_f32_e32 v12, v4, v4
	v_mul_f32_e32 v13, v5, v5
	v_mov_b32_e32 v14, v10
	v_mov_b32_e32 v15, v12
	v_mov_b32_e32 v12, v11
	v_add_f32_e32 v10, v14, v12
	v_add_f32_e32 v11, v15, v13
	v_add_f32_e32 v8, v8, v9
	v_add_f32_e32 v8, v8, v11
	v_add_f32_e32 v8, v10, v8
	v_lshlrev_b32_e32 v10, 16, v48
	v_and_b32_e32 v11, 0xffff0000, v48
	s_nop 1
	v_add_f32_dpp v8, v8, v8 quad_perm:[1,0,3,2] row_mask:0xf bank_mask:0xf
	s_nop 1
	v_add_f32_dpp v8, v8, v8 quad_perm:[2,3,0,1] row_mask:0xf bank_mask:0xf
	s_nop 1
	v_add_f32_dpp v8, v8, v8 row_half_mirror row_mask:0xf bank_mask:0xf
	v_fmamk_f32 v8, v8, 0x3c800000, v180
	v_mul_f32_e32 v9, 0x4b800000, v8
	v_cmp_gt_f32_e32 vcc, s1, v8
	s_nop 1
	v_cndmask_b32_e32 v8, v8, v9, vcc
	v_rsq_f32_e32 v8, v8
	s_nop 0
	v_mul_f32_e32 v9, 0x45800000, v8
	v_cndmask_b32_e32 v8, v8, v9, vcc
	v_mul_f32_e32 v0, v0, v8
	v_mul_f32_e32 v1, v1, v8
	v_mul_f32_e32 v2, v2, v8
	v_mul_f32_e32 v3, v3, v8
	v_mul_f32_e32 v0, v0, v10
	v_mul_f32_e32 v1, v1, v11
	v_lshlrev_b32_e32 v10, 16, v49
	v_and_b32_e32 v11, 0xffff0000, v49
	v_mul_f32_e32 v2, v2, v10
	v_mul_f32_e32 v3, v3, v11
	v_cvt_pk_bf16_f32 v0, v0, v1
	v_cvt_pk_bf16_f32 v1, v2, v3
	v_mul_f32_e32 v2, v4, v8
	v_mul_f32_e32 v3, v5, v8
	v_lshlrev_b32_e32 v4, 16, v50
	v_and_b32_e32 v5, 0xffff0000, v50
	v_mul_f32_e32 v2, v2, v4
	v_mul_f32_e32 v3, v3, v5
	v_mul_f32_e32 v4, v6, v8
	v_mul_f32_e32 v5, v7, v8
	v_lshlrev_b32_e32 v6, 16, v51
	v_and_b32_e32 v7, 0xffff0000, v51
	v_mul_f32_e32 v4, v4, v6
	v_mul_f32_e32 v5, v5, v7
	v_cvt_pk_bf16_f32 v2, v2, v3
	v_cvt_pk_bf16_f32 v3, v4, v5
	v_lshl_add_u64 v[4:5], s[26:27], 0, v[38:39]
	v_lshl_add_u64 v[4:5], v[4:5], 0, s[60:61]
	v_lshl_add_u64 v[4:5], v[4:5], 0, v[80:81]
	global_store_dwordx4 v[4:5], v[0:3], off sc1
	s_nop 1
	ds_read_b128 v[0:3], v16 offset:6528
	ds_read_b128 v[4:7], v16 offset:6544
	s_waitcnt lgkmcnt(1)
	v_mul_f32_e32 v8, v2, v2
	v_mul_f32_e32 v9, v3, v3
	v_mul_f32_e32 v10, v0, v0
	v_mul_f32_e32 v11, v1, v1
	s_nop 0
	v_pk_mov_b32 v[12:13], v[10:11], v[8:9] op_sel:[1,0]
	v_mov_b32_e32 v11, v9
	v_add_f32_e32 v8, v12, v10
	v_add_f32_e32 v9, v13, v11
	s_waitcnt lgkmcnt(0)
	v_mul_f32_e32 v10, v6, v6
	v_mul_f32_e32 v11, v7, v7
	v_mul_f32_e32 v12, v4, v4
	v_mul_f32_e32 v13, v5, v5
	v_mov_b32_e32 v14, v10
	v_mov_b32_e32 v15, v12
	v_mov_b32_e32 v12, v11
	v_add_f32_e32 v10, v14, v12
	v_add_f32_e32 v11, v15, v13
	v_add_f32_e32 v8, v8, v9
	v_add_f32_e32 v8, v8, v11
	v_add_f32_e32 v8, v10, v8
	v_lshlrev_b32_e32 v10, 16, v32
	v_and_b32_e32 v11, 0xffff0000, v32
	s_nop 1
	v_add_f32_dpp v8, v8, v8 quad_perm:[1,0,3,2] row_mask:0xf bank_mask:0xf
	s_nop 1
	v_add_f32_dpp v8, v8, v8 quad_perm:[2,3,0,1] row_mask:0xf bank_mask:0xf
	s_nop 1
	v_add_f32_dpp v8, v8, v8 row_half_mirror row_mask:0xf bank_mask:0xf
	v_fmamk_f32 v8, v8, 0x3c800000, v180
	v_mul_f32_e32 v9, 0x4b800000, v8
	v_cmp_gt_f32_e32 vcc, s1, v8
	s_nop 1
	v_cndmask_b32_e32 v8, v8, v9, vcc
	v_rsq_f32_e32 v8, v8
	s_nop 0
	v_mul_f32_e32 v9, 0x45800000, v8
	v_cndmask_b32_e32 v8, v8, v9, vcc
	v_mul_f32_e32 v0, v0, v8
	v_mul_f32_e32 v1, v1, v8
	v_mul_f32_e32 v2, v2, v8
	v_mul_f32_e32 v3, v3, v8
	v_mul_f32_e32 v0, v0, v10
	v_mul_f32_e32 v1, v1, v11
	v_lshlrev_b32_e32 v10, 16, v33
	v_and_b32_e32 v11, 0xffff0000, v33
	v_mul_f32_e32 v2, v2, v10
	v_mul_f32_e32 v3, v3, v11
	v_cvt_pk_bf16_f32 v0, v0, v1
	v_cvt_pk_bf16_f32 v1, v2, v3
	v_mul_f32_e32 v2, v4, v8
	v_mul_f32_e32 v3, v5, v8
	v_lshlrev_b32_e32 v4, 16, v34
	v_and_b32_e32 v5, 0xffff0000, v34
	v_mul_f32_e32 v2, v2, v4
	v_mul_f32_e32 v3, v3, v5
	v_mul_f32_e32 v4, v6, v8
	v_mul_f32_e32 v5, v7, v8
	v_lshlrev_b32_e32 v6, 16, v35
	v_and_b32_e32 v7, 0xffff0000, v35
	v_mul_f32_e32 v4, v4, v6
	v_mul_f32_e32 v5, v5, v7
	v_cvt_pk_bf16_f32 v2, v2, v3
	v_cvt_pk_bf16_f32 v3, v4, v5
	v_lshl_add_u64 v[4:5], s[26:27], 0, v[36:37]
	v_lshl_add_u64 v[4:5], v[4:5], 0, s[60:61]
	v_lshl_add_u64 v[4:5], v[4:5], 0, v[80:81]
	global_store_dwordx4 v[4:5], v[0:3], off sc1
	s_nop 1
	s_waitcnt vmcnt(0)
	s_barrier
